# v11 plus row-phase wave_sum butterflies via DPP (quad_perm/row_mirror) and permlane32_swap instead of ds_bpermute round trips
# baseline (speedup 1.0000x reference)
; #define GAS __attribute__((address_space(1)))
; __device__ __forceinline__ float wave_sum(float v) {
; #pragma unroll
;     for (int o = 1; o < 64; o <<= 1) v += __shfl_xor(v, o);
;     return v;
; }
; __device__ __forceinline__ void rows_norm(const Ctx& C, const float* x, const float* w, bf16* HN) {
;     const int gw = C.bid * NWAVES + C.wave, NGW = C.G * NWAVES;
;     for (int m = gw; m < T; m += NGW) {
;         const GAS f32x4* xr = (const GAS f32x4*)(x + (size_t)m * D) + C.lane; f32x4 v[8]; float s = 0.f;
; #pragma unroll
;         for (int j = 0; j < 8; ++j) { v[j] = xr[64 * j]; s += (v[j].x * v[j].x + v[j].y * v[j].y) + (v[j].z * v[j].z + v[j].w * v[j].w); }
;         const float rstd = 1.0f / sqrtf(wave_sum(s) * (1.0f / D) + EPS);
.LBB0_46:
	global_load_dwordx4 v[22:25], v[48:49], off offset:-4096
	global_load_dwordx4 v[6:9], v[48:49], off offset:-3072
	global_load_dwordx4 v[18:21], v[48:49], off offset:-2048
	global_load_dwordx4 v[10:13], v[48:49], off offset:1024
	global_load_dwordx4 v[26:29], v[48:49], off
	global_load_dwordx4 v[30:33], v[48:49], off offset:-1024
	global_load_dwordx4 v[2:5], v[48:49], off offset:3072
	global_load_dwordx4 v[14:17], v[48:49], off offset:2048
	global_load_dwordx4 v[56:59], v[36:37], off
	s_add_i32 s6, s6, s92
	v_lshl_add_u64 v[48:49], v[48:49], 0, s[24:25]
	s_cmpk_lt_i32 s6, 0x4000
	s_waitcnt vmcnt(8)
	v_mov_b32_e32 v62, v23
	s_waitcnt vmcnt(7)
	v_mov_b32_e32 v63, v7
	s_waitcnt vmcnt(6)
	v_pk_mul_f32 v[64:65], v[20:21], v[20:21]
	v_pk_mul_f32 v[66:67], v[18:19], v[18:19]
	s_waitcnt vmcnt(5)
	v_pk_mul_f32 v[68:69], v[12:13], v[12:13]
	v_pk_mul_f32 v[70:71], v[10:11], v[10:11]
	v_mov_b32_e32 v74, v25
	v_mov_b32_e32 v75, v9
	v_mov_b32_e32 v60, v22
	v_mov_b32_e32 v61, v6
	v_mov_b32_e32 v72, v24
	v_mov_b32_e32 v73, v8
	v_pk_mov_b32 v[84:85], v[66:67], v[64:65] op_sel:[1,0]
	v_mov_b32_e32 v67, v65
	v_pk_mov_b32 v[64:65], v[70:71], v[68:69] op_sel:[1,0]
	v_mov_b32_e32 v71, v69
	v_pk_mul_f32 v[62:63], v[62:63], v[62:63]
	v_pk_mul_f32 v[68:69], v[74:75], v[74:75]
	v_pk_fma_f32 v[60:61], v[60:61], v[60:61], v[62:63]
	v_pk_fma_f32 v[62:63], v[72:73], v[72:73], v[68:69]
	s_waitcnt vmcnt(3)
	v_mul_f32_e32 v76, v31, v31
	v_mul_f32_e32 v78, v33, v33
	v_pk_add_f32 v[66:67], v[84:85], v[66:67]
	v_pk_add_f32 v[60:61], v[60:61], v[62:63]
	v_mul_f32_e32 v83, v26, v26
	v_mul_f32_e32 v86, v28, v28
	v_mul_f32_e32 v87, v29, v29
	v_mul_f32_e32 v90, v27, v27
	v_pk_fma_f32 v[74:75], v[30:31], v[30:31], v[76:77] op_sel_hi:[1,1,0]
	v_pk_fma_f32 v[76:77], v[32:33], v[32:33], v[78:79] op_sel_hi:[1,1,0]
	v_pk_add_f32 v[66:67], v[66:67], v[66:67] op_sel:[0,1] op_sel_hi:[1,0]
	v_pk_add_f32 v[60:61], v[60:61], v[60:61] op_sel:[0,1] op_sel_hi:[1,0]
	v_mov_b32_e32 v75, v86
	v_mov_b32_e32 v77, v87
	v_mov_b32_e32 v67, v90
	v_mov_b32_e32 v61, v83
	v_pk_add_f32 v[62:63], v[74:75], v[76:77]
	v_pk_add_f32 v[60:61], v[60:61], v[66:67]
	s_waitcnt vmcnt(1)
	v_mul_f32_e32 v80, v15, v15
	v_mul_f32_e32 v82, v17, v17
	v_pk_add_f32 v[64:65], v[64:65], v[70:71]
	v_pk_add_f32 v[60:61], v[60:61], v[62:63]
	v_mul_f32_e32 v88, v4, v4
	v_mul_f32_e32 v89, v5, v5
	v_mul_f32_e32 v91, v2, v2
	v_mul_f32_e32 v92, v3, v3
	v_pk_fma_f32 v[78:79], v[14:15], v[14:15], v[80:81] op_sel_hi:[1,1,0]
	v_pk_fma_f32 v[80:81], v[16:17], v[16:17], v[82:83] op_sel_hi:[1,1,0]
	v_pk_add_f32 v[64:65], v[64:65], v[64:65] op_sel:[0,1] op_sel_hi:[1,0]
	v_pk_add_f32 v[60:61], v[60:61], v[60:61] op_sel:[0,1] op_sel_hi:[1,0]
	v_mov_b32_e32 v79, v88
	v_mov_b32_e32 v81, v89
	v_mov_b32_e32 v65, v92
	v_mov_b32_e32 v61, v91
	v_pk_add_f32 v[68:69], v[78:79], v[80:81]
	v_pk_add_f32 v[60:61], v[60:61], v[64:65]
	s_nop 0
	v_pk_add_f32 v[60:61], v[60:61], v[68:69]
	s_nop 0
	v_add_f32_e32 v60, v60, v61
	s_nop 1
	v_add_f32_dpp v60, v60, v60 quad_perm:[1,0,3,2] row_mask:0xf bank_mask:0xf
	s_nop 1
	v_add_f32_dpp v60, v60, v60 quad_perm:[2,3,0,1] row_mask:0xf bank_mask:0xf
	s_nop 1
	v_add_f32_dpp v60, v60, v60 row_half_mirror row_mask:0xf bank_mask:0xf
	s_nop 1
	v_add_f32_dpp v60, v60, v60 row_mirror row_mask:0xf bank_mask:0xf
	ds_bpermute_b32 v61, v53, v60
	s_waitcnt lgkmcnt(0)
; #define GAS __attribute__((address_space(1)))
; __device__ __forceinline__ unsigned pk2(float lo, float hi) { f32x2_t v = {lo, hi}; bf16x2_t b = __builtin_convertvector(v, bf16x2_t); return __builtin_bit_cast(unsigned, b); }
; __device__ __forceinline__ void rows_norm(const Ctx& C, const float* x, const float* w, bf16* HN) {
;     ...
;         const float rstd = 1.0f / sqrtf(wave_sum(s) * (1.0f / D) + EPS);
;         GAS v2u* o = (GAS v2u*)(HN + (size_t)m * D) + C.lane;
; #pragma unroll
;         for (int j = 0; j < 8; ++j) { const f32x4 ww = *((const GAS f32x4*)w + C.lane + 64 * j); o[64 * j] = (v2u){pk2(v[j].x * rstd * ww.x, v[j].y * rstd * ww.y), pk2(v[j].z * rstd * ww.z, v[j].w * rstd * ww.w)}; }
	v_add_f32_e32 v60, v60, v61
	v_mov_b32_e32 v61, v60
	s_nop 1
	v_permlane32_swap_b32_e32 v61, v60
	v_add_f32_e32 v60, v60, v61
	v_fmamk_f32 v60, v60, 0x3a000000, v1
	v_mul_f32_e32 v61, 0x4f800000, v60
	v_cmp_gt_f32_e32 vcc, s2, v60
	s_nop 1
	v_cndmask_b32_e32 v60, v60, v61, vcc
	v_sqrt_f32_e32 v61, v60
	s_nop 0
	v_add_u32_e32 v62, -1, v61
	v_add_u32_e32 v63, 1, v61
	v_fma_f32 v64, -v62, v61, v60
	v_fma_f32 v65, -v63, v61, v60
	v_cmp_ge_f32_e64 s[0:1], 0, v64
	s_nop 1
	v_cndmask_b32_e64 v61, v61, v62, s[0:1]
	v_cmp_lt_f32_e64 s[0:1], 0, v65
	s_nop 1
	v_cndmask_b32_e64 v61, v61, v63, s[0:1]
	v_mul_f32_e32 v62, 0x37800000, v61
	v_cndmask_b32_e32 v61, v61, v62, vcc
	v_cmp_class_f32_e32 vcc, v60, v55
	s_nop 1
	v_cndmask_b32_e32 v60, v61, v60, vcc
	v_div_scale_f32 v61, s[0:1], v60, v60, 1.0
	v_rcp_f32_e32 v63, v61
	v_div_scale_f32 v62, vcc, 1.0, v60, 1.0
	v_fma_f32 v64, -v61, v63, 1.0
	v_fmac_f32_e32 v63, v64, v63
	v_mul_f32_e32 v64, v62, v63
	v_fma_f32 v65, -v61, v64, v62
	v_fmac_f32_e32 v64, v65, v63
	v_fma_f32 v61, -v61, v64, v62
	v_div_fmas_f32 v61, v61, v63, v64
	v_div_fixup_f32 v60, v61, v60, 1.0
	v_pk_mul_f32 v[22:23], v[22:23], v[60:61] op_sel_hi:[1,0]
	v_pk_mul_f32 v[24:25], v[24:25], v[60:61] op_sel_hi:[1,0]
	s_waitcnt vmcnt(0)
	v_pk_mul_f32 v[22:23], v[56:57], v[22:23]
	v_pk_mul_f32 v[24:25], v[58:59], v[24:25]
	v_cvt_pk_bf16_f32 v22, v22, v23
	v_cvt_pk_bf16_f32 v23, v24, v25
	global_store_dwordx2 v[46:47], v[22:23], off
	global_load_dwordx4 v[22:25], v[36:37], off offset:1024
	v_pk_mul_f32 v[6:7], v[6:7], v[60:61] op_sel_hi:[1,0]
	v_pk_mul_f32 v[8:9], v[8:9], v[60:61] op_sel_hi:[1,0]
	v_pk_mul_f32 v[18:19], v[18:19], v[60:61] op_sel_hi:[1,0]
	v_pk_mul_f32 v[20:21], v[20:21], v[60:61] op_sel_hi:[1,0]
	v_pk_mul_f32 v[10:11], v[10:11], v[60:61] op_sel_hi:[1,0]
	v_pk_mul_f32 v[12:13], v[12:13], v[60:61] op_sel_hi:[1,0]
	v_pk_mul_f32 v[2:3], v[2:3], v[60:61] op_sel_hi:[1,0]
	v_pk_mul_f32 v[4:5], v[4:5], v[60:61] op_sel_hi:[1,0]
	s_waitcnt vmcnt(0)
	v_pk_mul_f32 v[6:7], v[22:23], v[6:7]
	v_pk_mul_f32 v[8:9], v[24:25], v[8:9]
	v_cvt_pk_bf16_f32 v6, v6, v7
	v_cvt_pk_bf16_f32 v7, v8, v9
	global_store_dwordx2 v[46:47], v[6:7], off offset:512
	global_load_dwordx4 v[6:9], v[36:37], off offset:2048
	s_waitcnt vmcnt(0)
	v_pk_mul_f32 v[6:7], v[6:7], v[18:19]
	v_pk_mul_f32 v[8:9], v[8:9], v[20:21]
	v_cvt_pk_bf16_f32 v6, v6, v7
	v_cvt_pk_bf16_f32 v7, v8, v9
	global_store_dwordx2 v[46:47], v[6:7], off offset:1024
	global_load_dwordx4 v[6:9], v[36:37], off offset:3072
	v_pk_mul_f32 v[18:19], v[30:31], v[60:61] op_sel_hi:[1,0]
	v_pk_mul_f32 v[20:21], v[32:33], v[60:61] op_sel_hi:[1,0]
	s_waitcnt vmcnt(0)
	v_pk_mul_f32 v[6:7], v[6:7], v[18:19]
	v_pk_mul_f32 v[8:9], v[8:9], v[20:21]
	v_cvt_pk_bf16_f32 v6, v6, v7
	v_cvt_pk_bf16_f32 v7, v8, v9
	global_store_dwordx2 v[46:47], v[6:7], off offset:1536
	global_load_dwordx4 v[6:9], v[38:39], off
	v_pk_mul_f32 v[18:19], v[26:27], v[60:61] op_sel_hi:[1,0]
	v_pk_mul_f32 v[20:21], v[28:29], v[60:61] op_sel_hi:[1,0]
	s_waitcnt vmcnt(0)
	v_pk_mul_f32 v[6:7], v[18:19], v[6:7]
	v_pk_mul_f32 v[8:9], v[20:21], v[8:9]
	v_cvt_pk_bf16_f32 v6, v6, v7
	v_cvt_pk_bf16_f32 v7, v8, v9
	global_store_dwordx2 v[46:47], v[6:7], off offset:2048
	global_load_dwordx4 v[6:9], v[40:41], off
	s_waitcnt vmcnt(0)
	v_pk_mul_f32 v[6:7], v[10:11], v[6:7]
	v_pk_mul_f32 v[8:9], v[12:13], v[8:9]
	v_cvt_pk_bf16_f32 v6, v6, v7
	v_cvt_pk_bf16_f32 v7, v8, v9
	global_store_dwordx2 v[46:47], v[6:7], off offset:2560
	global_load_dwordx4 v[6:9], v[42:43], off
	v_pk_mul_f32 v[10:11], v[14:15], v[60:61] op_sel_hi:[1,0]
	v_pk_mul_f32 v[12:13], v[16:17], v[60:61] op_sel_hi:[1,0]
	s_waitcnt vmcnt(0)
	v_pk_mul_f32 v[6:7], v[10:11], v[6:7]
	v_pk_mul_f32 v[8:9], v[12:13], v[8:9]
	v_cvt_pk_bf16_f32 v6, v6, v7
	v_cvt_pk_bf16_f32 v7, v8, v9
	global_store_dwordx2 v[46:47], v[6:7], off offset:3072
	global_load_dwordx4 v[6:9], v[44:45], off
	s_waitcnt vmcnt(0)
	v_pk_mul_f32 v[2:3], v[2:3], v[6:7]
	v_pk_mul_f32 v[4:5], v[4:5], v[8:9]
	v_cvt_pk_bf16_f32 v2, v2, v3
	v_cvt_pk_bf16_f32 v3, v4, v5
	global_store_dwordx2 v[46:47], v[2:3], off offset:3584
	v_lshl_add_u64 v[46:47], v[46:47], 0, s[12:13]
	s_cbranch_scc1 .LBB0_46

; #define GAS __attribute__((address_space(1)))
; __device__ __forceinline__ unsigned pk2(float lo, float hi) { f32x2_t v = {lo, hi}; bf16x2_t b = __builtin_convertvector(v, bf16x2_t); return __builtin_bit_cast(unsigned, b); }
; __device__ __forceinline__ float bflo(unsigned u) { return __uint_as_float(u << 16); }
; __device__ __forceinline__ float bfhi(unsigned u) { return __uint_as_float(u & 0xffff0000u); }
; template <bool XIN_BF, bool XOUT_BF>
; __device__ __forceinline__ void rows_update_g(const Ctx& C, const float* xin, const bf16* xin_bf, const bf16* Y, const float* wpost, float scale, float* xout, bf16* xout_bf, const float* wpre, bf16* HN) {
;     ...
;     for (int m = gw; m < T; m += NGW) {
;         const GAS v2u* yr = (const GAS v2u*)(Y + (size_t)m * D) + C.lane;
;         f32x4 v[8]; float s = 0.f;
; #pragma unroll
;         for (int j = 0; j < 8; ++j) { const v2u w = yr[64 * j]; v[j] = (f32x4){bflo(w.x), bfhi(w.x), bflo(w.y), bfhi(w.y)}; s += (v[j].x * v[j].x + v[j].y * v[j].y) + (v[j].z * v[j].z + v[j].w * v[j].w); }
;         const float rstd = scale / sqrtf(wave_sum(s) * (1.0f / D) + EPS);
;         float s2 = 0.f;
; #pragma unroll
;         for (int j = 0; j < 8; ++j) { const f32x4 ww = *((const GAS f32x4*)wpost + C.lane + 64 * j); f32x4 xv;
;             if (XIN_BF) { const v2u xw = *((const GAS v2u*)(xin_bf + (size_t)m * D) + C.lane + 64 * j); xv = (f32x4){bflo(xw.x), bfhi(xw.x), bflo(xw.y), bfhi(xw.y)}; }
;             else xv = *((const GAS f32x4*)(xin + (size_t)m * D) + C.lane + 64 * j);
;             v[j] = xv + v[j] * rstd * ww;
;             if (XOUT_BF) { const v2u ow = (v2u){pk2(v[j].x, v[j].y), pk2(v[j].z, v[j].w)}; *((GAS v2u*)(xout_bf + (size_t)m * D) + C.lane + 64 * j) = ow;
.LBB0_207:
	v_lshl_add_u64 v[24:25], s[0:1], 0, v[20:21]
	v_add_co_u32_e32 v26, vcc, 0x19100000, v24
	s_nop 1
	v_addc_co_u32_e32 v27, vcc, 0, v25, vcc
	global_load_dwordx2 v[34:35], v[26:27], off
	global_load_dwordx2 v[36:37], v[26:27], off offset:512
	global_load_dwordx2 v[38:39], v[26:27], off offset:1024
	global_load_dwordx2 v[40:41], v[26:27], off offset:1536
	global_load_dwordx2 v[50:51], v[26:27], off offset:2048
	global_load_dwordx2 v[52:53], v[26:27], off offset:2560
	global_load_dwordx2 v[54:55], v[26:27], off offset:3072
	global_load_dwordx2 v[56:57], v[26:27], off offset:3584
	s_nop 0
	global_load_dwordx4 v[26:29], v[0:1], off
	global_load_dwordx4 v[30:33], v[22:23], off offset:-4096
	s_waitcnt vmcnt(9)
	v_lshlrev_b32_e32 v58, 16, v34
	v_and_b32_e32 v59, 0xffff0000, v34
	v_lshlrev_b32_e32 v34, 16, v35
	v_and_b32_e32 v35, 0xffff0000, v35
	s_waitcnt vmcnt(6)
	v_lshlrev_b32_e32 v65, 16, v40
	v_lshlrev_b32_e32 v61, 16, v37
	v_lshlrev_b32_e32 v60, 16, v36
	v_and_b32_e32 v37, 0xffff0000, v37
	v_and_b32_e32 v36, 0xffff0000, v36
	s_waitcnt vmcnt(4)
	v_lshlrev_b32_e32 v71, 16, v53
	v_lshlrev_b32_e32 v70, 16, v52
	v_and_b32_e32 v73, 0xffff0000, v53
	v_and_b32_e32 v72, 0xffff0000, v52
	v_mul_f32_e32 v52, v35, v35
	v_mul_f32_e32 v64, v59, v59
	v_mov_b32_e32 v53, v65
	v_lshlrev_b32_e32 v62, 16, v38
	v_and_b32_e32 v63, 0xffff0000, v38
	v_lshlrev_b32_e32 v38, 16, v39
	v_and_b32_e32 v39, 0xffff0000, v39
	s_waitcnt vmcnt(2)
	v_lshlrev_b32_e32 v77, 16, v56
	v_and_b32_e32 v79, 0xffff0000, v56
	v_lshlrev_b32_e32 v80, 16, v57
	v_and_b32_e32 v81, 0xffff0000, v57
	v_pk_mul_f32 v[56:57], v[36:37], v[36:37]
	v_pk_fma_f32 v[90:91], v[34:35], v[34:35], v[52:53] op_sel_hi:[1,1,0]
	v_pk_fma_f32 v[92:93], v[58:59], v[58:59], v[64:65] op_sel_hi:[1,1,0]
	v_and_b32_e32 v67, 0xffff0000, v40
	v_lshlrev_b32_e32 v40, 16, v41
	v_and_b32_e32 v41, 0xffff0000, v41
	v_mul_f32_e32 v66, v63, v63
	v_mul_f32_e32 v76, v39, v39
	v_pk_fma_f32 v[56:57], v[60:61], v[60:61], v[56:57]
	v_mov_b32_e32 v64, v92
	v_mov_b32_e32 v52, v90
	v_mul_f32_e32 v86, v67, v67
	v_mul_f32_e32 v89, v40, v40
	v_mul_f32_e32 v100, v41, v41
	v_pk_fma_f32 v[94:95], v[62:63], v[62:63], v[66:67] op_sel_hi:[1,1,0]
	v_pk_fma_f32 v[96:97], v[38:39], v[38:39], v[76:77] op_sel_hi:[1,1,0]
	v_pk_add_f32 v[90:91], v[92:93], v[90:91]
	v_pk_add_f32 v[56:57], v[56:57], v[56:57] op_sel:[0,1] op_sel_hi:[1,0]
	v_pk_mul_f32 v[52:53], v[64:65], v[52:53]
	v_lshlrev_b32_e32 v69, 16, v51
	v_lshlrev_b32_e32 v68, 16, v50
	v_and_b32_e32 v51, 0xffff0000, v51
	v_and_b32_e32 v50, 0xffff0000, v50
	v_mov_b32_e32 v95, v89
	v_mov_b32_e32 v97, v100
	v_mov_b32_e32 v57, v86
	v_mov_b32_e32 v91, v53
	v_pk_mul_f32 v[82:83], v[50:51], v[50:51]
	v_pk_add_f32 v[92:93], v[94:95], v[96:97]
	v_pk_add_f32 v[52:53], v[90:91], v[56:57]
	v_pk_fma_f32 v[82:83], v[68:69], v[68:69], v[82:83]
	v_pk_add_f32 v[52:53], v[52:53], v[92:93]
	v_pk_add_f32 v[82:83], v[82:83], v[82:83] op_sel:[0,1] op_sel_hi:[1,0]
	v_pk_add_f32 v[52:53], v[52:53], v[52:53] op_sel:[0,1] op_sel_hi:[1,0]
	v_lshlrev_b32_e32 v74, 16, v54
	v_and_b32_e32 v75, 0xffff0000, v54
	v_lshlrev_b32_e32 v54, 16, v55
	v_and_b32_e32 v55, 0xffff0000, v55
	v_pk_mul_f32 v[84:85], v[72:73], v[72:73]
	v_mov_b32_e32 v87, v77
	v_mov_b32_e32 v86, v82
	v_mov_b32_e32 v76, v52
	v_mul_f32_e32 v78, v75, v75
	v_mul_f32_e32 v88, v55, v55
	v_pk_fma_f32 v[84:85], v[70:71], v[70:71], v[84:85]
	v_pk_add_f32 v[52:53], v[52:53], v[82:83]
	v_pk_mul_f32 v[56:57], v[76:77], v[86:87]
	v_mul_f32_e32 v101, v79, v79
	v_mul_f32_e32 v102, v80, v80
	v_mul_f32_e32 v103, v81, v81
	v_pk_fma_f32 v[98:99], v[74:75], v[74:75], v[78:79] op_sel_hi:[1,1,0]
	v_pk_add_f32 v[84:85], v[84:85], v[84:85] op_sel:[0,1] op_sel_hi:[1,0]
	v_mov_b32_e32 v53, v57
	v_pk_fma_f32 v[56:57], v[54:55], v[54:55], v[88:89] op_sel_hi:[1,1,0]
	v_mov_b32_e32 v99, v102
	v_mov_b32_e32 v85, v101
	v_mov_b32_e32 v57, v103
	v_pk_add_f32 v[52:53], v[52:53], v[84:85]
	v_pk_add_f32 v[56:57], v[98:99], v[56:57]
	v_lshl_add_u64 v[82:83], s[22:23], 0, v[20:21]
	v_pk_add_f32 v[52:53], v[52:53], v[56:57]
	v_mov_b32_e32 v78, v77
	v_add_f32_e32 v52, v52, v53
	s_nop 1
	v_add_f32_dpp v52, v52, v52 quad_perm:[1,0,3,2] row_mask:0xf bank_mask:0xf
	s_nop 1
	v_add_f32_dpp v52, v52, v52 quad_perm:[2,3,0,1] row_mask:0xf bank_mask:0xf
	s_nop 1
	v_add_f32_dpp v52, v52, v52 row_half_mirror row_mask:0xf bank_mask:0xf
	s_nop 1
	v_add_f32_dpp v52, v52, v52 row_mirror row_mask:0xf bank_mask:0xf
	ds_bpermute_b32 v53, v46, v52
	s_waitcnt lgkmcnt(0)
	v_add_f32_e32 v52, v52, v53
	v_mov_b32_e32 v53, v52
	s_nop 1
	v_permlane32_swap_b32_e32 v53, v52
	v_add_f32_e32 v52, v52, v53
	v_fmamk_f32 v52, v52, 0x3a000000, v48
	v_mul_f32_e32 v53, 0x4f800000, v52
	v_cmp_gt_f32_e32 vcc, s3, v52
	s_nop 1
	v_cndmask_b32_e32 v52, v52, v53, vcc
	v_sqrt_f32_e32 v53, v52
	s_nop 0
	v_add_u32_e32 v56, -1, v53
	v_add_u32_e32 v57, 1, v53
	v_fma_f32 v64, -v56, v53, v52
	v_fma_f32 v66, -v57, v53, v52
	v_cmp_ge_f32_e64 s[6:7], 0, v64
	s_nop 1
	v_cndmask_b32_e64 v53, v53, v56, s[6:7]
	v_cmp_lt_f32_e64 s[6:7], 0, v66
	s_nop 1
	v_cndmask_b32_e64 v53, v53, v57, s[6:7]
	v_mul_f32_e32 v56, 0x37800000, v53
	v_cndmask_b32_e32 v53, v53, v56, vcc
	v_cmp_class_f32_e32 vcc, v52, v49
	s_nop 1
	v_cndmask_b32_e32 v52, v53, v52, vcc
	v_div_scale_f32 v53, s[6:7], v52, v52, 0.5
	v_rcp_f32_e32 v56, v53
	v_div_scale_f32 v57, vcc, 0.5, v52, 0.5
	v_fma_f32 v64, -v53, v56, 1.0
	v_fmac_f32_e32 v56, v64, v56
	v_mul_f32_e32 v64, v57, v56
	v_fma_f32 v66, -v53, v64, v57
	v_fmac_f32_e32 v64, v66, v56
	v_fma_f32 v53, -v53, v64, v57
	v_div_fmas_f32 v53, v53, v56, v64
	v_div_fixup_f32 v64, v53, v52, 0.5
	v_pk_mul_f32 v[52:53], v[64:65], v[58:59] op_sel_hi:[0,1]
	v_pk_mul_f32 v[34:35], v[64:65], v[34:35] op_sel_hi:[0,1]
	s_waitcnt vmcnt(0)
; #define GAS __attribute__((address_space(1)))
; __device__ __forceinline__ unsigned pk2(float lo, float hi) { f32x2_t v = {lo, hi}; bf16x2_t b = __builtin_convertvector(v, bf16x2_t); return __builtin_bit_cast(unsigned, b); }
; __device__ __forceinline__ float bflo(unsigned u) { return __uint_as_float(u << 16); }
; __device__ __forceinline__ float bfhi(unsigned u) { return __uint_as_float(u & 0xffff0000u); }
; template <bool XIN_BF, bool XOUT_BF>
; __device__ __forceinline__ void rows_update_g(const Ctx& C, const float* xin, const bf16* xin_bf, const bf16* Y, const float* wpost, float scale, float* xout, bf16* xout_bf, const float* wpre, bf16* HN) {
;     ...
;         for (int j = 0; j < 8; ++j) { const f32x4 ww = *((const GAS f32x4*)wpost + C.lane + 64 * j); f32x4 xv;
;             if (XIN_BF) { const v2u xw = *((const GAS v2u*)(xin_bf + (size_t)m * D) + C.lane + 64 * j); xv = (f32x4){bflo(xw.x), bfhi(xw.x), bflo(xw.y), bfhi(xw.y)}; }
;             else xv = *((const GAS f32x4*)(xin + (size_t)m * D) + C.lane + 64 * j);
;             v[j] = xv + v[j] * rstd * ww;
;             if (XOUT_BF) { const v2u ow = (v2u){pk2(v[j].x, v[j].y), pk2(v[j].z, v[j].w)}; *((GAS v2u*)(xout_bf + (size_t)m * D) + C.lane + 64 * j) = ow;
;                 v[j] = (f32x4){bflo(ow.x), bfhi(ow.x), bflo(ow.y), bfhi(ow.y)}; }
;             else *((GAS f32x4*)(xout + (size_t)m * D) + C.lane + 64 * j) = v[j];
;             s2 += (v[j].x * v[j].x + v[j].y * v[j].y) + (v[j].z * v[j].z + v[j].w * v[j].w); }
;         if (wpre) { const float r2 = 1.0f / sqrtf(wave_sum(s2) * (1.0f / D) + EPS);
	v_pk_fma_f32 v[28:29], v[28:29], v[34:35], v[32:33]
	v_pk_fma_f32 v[26:27], v[26:27], v[52:53], v[30:31]
	v_mov_b32_e32 v52, v60
	v_cvt_pk_bf16_f32 v26, v26, v27
	v_cvt_pk_bf16_f32 v27, v28, v29
	global_store_dwordx2 v[82:83], v[26:27], off
	global_load_dwordx4 v[28:31], v[0:1], off offset:1024
	global_load_dwordx4 v[32:35], v[22:23], off offset:-3072
	v_mov_b32_e32 v53, v36
	v_mov_b32_e32 v36, v61
	v_pk_mul_f32 v[52:53], v[64:65], v[52:53] op_sel_hi:[0,1]
	v_pk_mul_f32 v[36:37], v[64:65], v[36:37] op_sel_hi:[0,1]
	v_pk_mul_f32 v[38:39], v[64:65], v[38:39] op_sel_hi:[0,1]
	v_mov_b32_e32 v66, v65
	v_pk_mul_f32 v[40:41], v[40:41], v[64:65] op_sel_hi:[1,0]
	v_pk_mul_f32 v[54:55], v[64:65], v[54:55] op_sel_hi:[0,1]
	v_pk_mul_f32 v[58:59], v[80:81], v[64:65] op_sel_hi:[1,0]
	s_and_b64 vcc, exec, s[4:5]
	s_waitcnt vmcnt(0)
	v_pk_fma_f32 v[30:31], v[30:31], v[36:37], v[34:35]
	v_pk_fma_f32 v[28:29], v[28:29], v[52:53], v[32:33]
	v_pk_mul_f32 v[52:53], v[64:65], v[62:63] op_sel_hi:[0,1]
	v_cvt_pk_bf16_f32 v28, v28, v29
	v_cvt_pk_bf16_f32 v29, v30, v31
	global_store_dwordx2 v[82:83], v[28:29], off offset:512
	global_load_dwordx4 v[30:33], v[0:1], off offset:2048
	global_load_dwordx4 v[34:37], v[22:23], off offset:-2048
	s_waitcnt vmcnt(0)
	v_pk_fma_f32 v[32:33], v[32:33], v[38:39], v[36:37]
	v_pk_fma_f32 v[30:31], v[30:31], v[52:53], v[34:35]
	v_pk_mul_f32 v[52:53], v[66:67], v[64:65] op_sel_hi:[1,0]
	v_cvt_pk_bf16_f32 v30, v30, v31
	v_cvt_pk_bf16_f32 v31, v32, v33
	global_store_dwordx2 v[82:83], v[30:31], off offset:1024
	global_load_dwordx4 v[32:35], v[0:1], off offset:3072
	global_load_dwordx4 v[36:39], v[22:23], off offset:-1024
	s_waitcnt vmcnt(0)
	v_pk_fma_f32 v[34:35], v[34:35], v[40:41], v[38:39]
	v_pk_fma_f32 v[32:33], v[32:33], v[52:53], v[36:37]
	v_mov_b32_e32 v52, v68
	v_cvt_pk_bf16_f32 v32, v32, v33
	v_cvt_pk_bf16_f32 v33, v34, v35
	global_store_dwordx2 v[82:83], v[32:33], off offset:1536
	global_load_dwordx4 v[34:37], v[2:3], off
	global_load_dwordx4 v[38:41], v[22:23], off
	v_mov_b32_e32 v53, v50
	v_mov_b32_e32 v50, v69
	v_pk_mul_f32 v[52:53], v[64:65], v[52:53] op_sel_hi:[0,1]
	v_pk_mul_f32 v[50:51], v[64:65], v[50:51] op_sel_hi:[0,1]
	s_waitcnt vmcnt(0)
	v_pk_fma_f32 v[36:37], v[36:37], v[50:51], v[40:41]
	v_pk_fma_f32 v[34:35], v[34:35], v[52:53], v[38:39]
	v_mov_b32_e32 v40, v70
	v_cvt_pk_bf16_f32 v34, v34, v35
	v_cvt_pk_bf16_f32 v35, v36, v37
	global_store_dwordx2 v[82:83], v[34:35], off offset:2048
	global_load_dwordx4 v[36:39], v[4:5], off
	global_load_dwordx4 v[50:53], v[22:23], off offset:1024
	v_mov_b32_e32 v41, v72
	v_mov_b32_e32 v72, v71
	v_pk_mul_f32 v[40:41], v[64:65], v[40:41] op_sel_hi:[0,1]
	v_pk_mul_f32 v[56:57], v[64:65], v[72:73] op_sel_hi:[0,1]
	s_waitcnt vmcnt(0)
	v_pk_fma_f32 v[38:39], v[56:57], v[38:39], v[52:53]
	v_pk_fma_f32 v[36:37], v[40:41], v[36:37], v[50:51]
	v_pk_mul_f32 v[56:57], v[64:65], v[74:75] op_sel_hi:[0,1]
	v_cvt_pk_bf16_f32 v36, v36, v37
	v_cvt_pk_bf16_f32 v37, v38, v39
	global_store_dwordx2 v[82:83], v[36:37], off offset:2560
	global_load_dwordx4 v[38:41], v[6:7], off
	global_load_dwordx4 v[50:53], v[22:23], off offset:2048
	s_waitcnt vmcnt(0)
	v_pk_fma_f32 v[40:41], v[54:55], v[40:41], v[52:53]
	v_pk_fma_f32 v[38:39], v[56:57], v[38:39], v[50:51]
	s_nop 0
	v_cvt_pk_bf16_f32 v38, v38, v39
	v_cvt_pk_bf16_f32 v39, v40, v41
	global_store_dwordx2 v[82:83], v[38:39], off offset:3072
	global_load_dwordx4 v[50:53], v[8:9], off
	global_load_dwordx4 v[54:57], v[22:23], off offset:3072
	v_pk_mul_f32 v[40:41], v[78:79], v[64:65] op_sel_hi:[1,0]
	s_waitcnt vmcnt(0)
	v_pk_fma_f32 v[52:53], v[58:59], v[52:53], v[56:57]
	v_pk_fma_f32 v[40:41], v[40:41], v[50:51], v[54:55]
	s_nop 0
	v_cvt_pk_bf16_f32 v40, v40, v41
	v_cvt_pk_bf16_f32 v41, v52, v53
	global_store_dwordx2 v[82:83], v[40:41], off offset:3584
	s_cbranch_vccnz .LBB0_206
	v_lshlrev_b32_e32 v59, 16, v31
	v_lshlrev_b32_e32 v58, 16, v30
	v_and_b32_e32 v31, 0xffff0000, v31
	v_and_b32_e32 v30, 0xffff0000, v30
	v_lshlrev_b32_e32 v50, 16, v26
	v_and_b32_e32 v51, 0xffff0000, v26
	v_lshlrev_b32_e32 v52, 16, v27
	v_and_b32_e32 v53, 0xffff0000, v27
	v_pk_mul_f32 v[26:27], v[30:31], v[30:31]
	v_lshlrev_b32_e32 v62, 16, v32
	v_pk_fma_f32 v[26:27], v[58:59], v[58:59], v[26:27]
	v_and_b32_e32 v63, 0xffff0000, v32
	v_lshlrev_b32_e32 v32, 16, v33
	v_pk_add_f32 v[60:61], v[26:27], v[26:27] op_sel_hi:[0,1]
	v_and_b32_e32 v33, 0xffff0000, v33
	v_mul_f32_e32 v26, v32, v32
	v_and_b32_e32 v69, 0xffff0000, v36
	v_and_b32_e32 v57, 0xffff0000, v29
	v_pk_fma_f32 v[64:65], v[32:33], v[32:33], v[26:27] op_sel_hi:[1,1,0]
	v_lshlrev_b32_e32 v68, 16, v36
	v_mul_f32_e32 v26, v69, v69
	v_lshlrev_b32_e32 v36, 16, v37
	v_and_b32_e32 v37, 0xffff0000, v37
	v_and_b32_e32 v55, 0xffff0000, v28
	v_lshlrev_b32_e32 v56, 16, v29
	v_pk_fma_f32 v[70:71], v[68:69], v[68:69], v[26:27] op_sel_hi:[1,1,0]
	v_mul_f32_e32 v26, v37, v37
	v_and_b32_e32 v75, 0xffff0000, v38
	v_mov_b32_e32 v86, v53
	v_mov_b32_e32 v87, v57
	v_lshlrev_b32_e32 v54, 16, v28
	v_pk_fma_f32 v[72:73], v[36:37], v[36:37], v[26:27] op_sel_hi:[1,1,0]
	v_lshlrev_b32_e32 v74, 16, v38
	v_mul_f32_e32 v26, v75, v75
	v_lshlrev_b32_e32 v38, 16, v39
	v_and_b32_e32 v39, 0xffff0000, v39
	v_mov_b32_e32 v84, v52
	v_mov_b32_e32 v85, v56
	v_pk_mul_f32 v[86:87], v[86:87], v[86:87]
	v_mov_b32_e32 v88, v51
	v_mov_b32_e32 v89, v55
	v_pk_fma_f32 v[76:77], v[74:75], v[74:75], v[26:27] op_sel_hi:[1,1,0]
	v_mul_f32_e32 v26, v39, v39
	v_pk_fma_f32 v[84:85], v[84:85], v[84:85], v[86:87]
	v_mov_b32_e32 v86, v50
	v_mov_b32_e32 v87, v54
	v_pk_mul_f32 v[88:89], v[88:89], v[88:89]
	v_pk_fma_f32 v[78:79], v[38:39], v[38:39], v[26:27] op_sel_hi:[1,1,0]
; #define GAS __attribute__((address_space(1)))
; __device__ __forceinline__ unsigned pk2(float lo, float hi) { f32x2_t v = {lo, hi}; bf16x2_t b = __builtin_convertvector(v, bf16x2_t); return __builtin_bit_cast(unsigned, b); }
; template <bool XIN_BF, bool XOUT_BF>
; __device__ __forceinline__ void rows_update_g(const Ctx& C, const float* xin, const bf16* xin_bf, const bf16* Y, const float* wpost, float scale, float* xout, bf16* xout_bf, const float* wpre, bf16* HN) {
;     ...
;             s2 += (v[j].x * v[j].x + v[j].y * v[j].y) + (v[j].z * v[j].z + v[j].w * v[j].w); }
;         if (wpre) { const float r2 = 1.0f / sqrtf(wave_sum(s2) * (1.0f / D) + EPS);
;             GAS v2u* o = (GAS v2u*)(HN + (size_t)m * D) + C.lane;
; #pragma unroll
;             for (int j = 0; j < 8; ++j) { const f32x4 ww = *((const GAS f32x4*)wpre + C.lane + 64 * j); o[64 * j] = (v2u){pk2(v[j].x * r2 * ww.x, v[j].y * r2 * ww.y), pk2(v[j].z * r2 * ww.z, v[j].w * r2 * ww.w)}; } }
	global_load_dwordx4 v[26:29], v[10:11], off
	v_pk_fma_f32 v[86:87], v[86:87], v[86:87], v[88:89]
	v_lshlrev_b32_e32 v66, 16, v34
	v_and_b32_e32 v67, 0xffff0000, v34
	v_lshlrev_b32_e32 v34, 16, v35
	v_and_b32_e32 v35, 0xffff0000, v35
	v_pk_add_f32 v[84:85], v[86:87], v[84:85]
	v_pk_mul_f32 v[86:87], v[34:35], v[34:35]
	v_pk_add_f32 v[84:85], v[84:85], v[84:85] op_sel_hi:[0,1]
	v_mov_b32_e32 v60, v86
	v_mov_b32_e32 v84, v87
	v_mul_f32_e32 v86, v62, v62
	v_pk_add_f32 v[60:61], v[60:61], v[84:85]
	v_pk_mul_f32 v[84:85], v[66:67], v[66:67]
	v_pk_fma_f32 v[86:87], v[62:63], v[62:63], v[86:87] op_sel_hi:[1,1,0]
	v_mov_b32_e32 v64, v85
	v_mov_b32_e32 v85, v87
	v_lshlrev_b32_e32 v80, 16, v40
	v_and_b32_e32 v83, 0xffff0000, v40
	v_and_b32_e32 v82, s0, v40
	v_lshlrev_b32_e32 v40, 16, v41
	v_and_b32_e32 v41, 0xffff0000, v41
	v_pk_add_f32 v[64:65], v[84:85], v[64:65]
	v_pk_add_f32 v[70:71], v[70:71], v[72:73]
	v_pk_add_f32 v[60:61], v[64:65], v[60:61]
	v_pk_mul_f32 v[64:65], v[40:41], v[40:41]
	v_pk_add_f32 v[60:61], v[60:61], v[60:61] op_sel:[0,1] op_sel_hi:[1,0]
	v_mov_b32_e32 v77, v64
	v_mov_b32_e32 v79, v65
	v_pk_add_f32 v[64:65], v[76:77], v[78:79]
	v_pk_mul_f32 v[76:77], v[82:83], v[82:83]
	v_mul_f32_e32 v71, v80, v80
	v_mov_b32_e32 v61, v77
	v_pk_add_f32 v[60:61], v[70:71], v[60:61]
	v_mov_b32_e32 v81, v83
	v_pk_add_f32 v[60:61], v[60:61], v[64:65]
	s_nop 0
	v_add_f32_e32 v60, v60, v61
	s_nop 1
	v_add_f32_dpp v60, v60, v60 quad_perm:[1,0,3,2] row_mask:0xf bank_mask:0xf
	s_nop 1
	v_add_f32_dpp v60, v60, v60 quad_perm:[2,3,0,1] row_mask:0xf bank_mask:0xf
	s_nop 1
	v_add_f32_dpp v60, v60, v60 row_half_mirror row_mask:0xf bank_mask:0xf
	s_nop 1
	v_add_f32_dpp v60, v60, v60 row_mirror row_mask:0xf bank_mask:0xf
	ds_bpermute_b32 v61, v46, v60
	s_waitcnt lgkmcnt(0)
	v_add_f32_e32 v60, v60, v61
	v_mov_b32_e32 v61, v60
	s_nop 1
	v_permlane32_swap_b32_e32 v61, v60
	v_add_f32_e32 v60, v60, v61
	v_fmamk_f32 v60, v60, 0x3a000000, v48
	v_mul_f32_e32 v61, 0x4f800000, v60
	v_cmp_gt_f32_e32 vcc, s3, v60
	s_nop 1
	v_cndmask_b32_e32 v60, v60, v61, vcc
	v_sqrt_f32_e32 v61, v60
	s_nop 0
	v_add_u32_e32 v64, -1, v61
	v_fma_f32 v65, -v64, v61, v60
	v_cmp_ge_f32_e64 s[6:7], 0, v65
	v_add_u32_e32 v65, 1, v61
	s_nop 0
	v_cndmask_b32_e64 v64, v61, v64, s[6:7]
	v_fma_f32 v61, -v65, v61, v60
	v_cmp_lt_f32_e64 s[6:7], 0, v61
	s_nop 1
	v_cndmask_b32_e64 v61, v64, v65, s[6:7]
	v_mul_f32_e32 v64, 0x37800000, v61
	v_cndmask_b32_e32 v61, v61, v64, vcc
	v_cmp_class_f32_e32 vcc, v60, v49
	s_nop 1
	v_cndmask_b32_e32 v60, v61, v60, vcc
	v_div_scale_f32 v61, s[6:7], v60, v60, 1.0
	v_rcp_f32_e32 v64, v61
	s_nop 0
	v_fma_f32 v65, -v61, v64, 1.0
	v_fmac_f32_e32 v64, v65, v64
	v_div_scale_f32 v65, vcc, 1.0, v60, 1.0
	v_mul_f32_e32 v70, v65, v64
	v_fma_f32 v71, -v61, v70, v65
	v_fmac_f32_e32 v70, v71, v64
	v_fma_f32 v61, -v61, v70, v65
	v_div_fmas_f32 v61, v61, v64, v70
	v_div_fixup_f32 v60, v61, v60, 1.0
	v_pk_mul_f32 v[50:51], v[60:61], v[50:51] op_sel_hi:[0,1]
	s_waitcnt vmcnt(0)
	v_pk_mul_f32 v[26:27], v[26:27], v[50:51]
	v_pk_mul_f32 v[50:51], v[60:61], v[52:53] op_sel_hi:[0,1]
	v_pk_mul_f32 v[28:29], v[28:29], v[50:51]
	v_cvt_pk_bf16_f32 v26, v26, v27
	v_cvt_pk_bf16_f32 v27, v28, v29
	v_add_co_u32_e32 v28, vcc, s28, v24
	v_pk_mul_f32 v[50:51], v[60:61], v[54:55] op_sel_hi:[0,1]
	s_nop 0
	v_addc_co_u32_e32 v29, vcc, 0, v25, vcc
	global_store_dwordx2 v[28:29], v[26:27], off
	global_load_dwordx4 v[24:27], v[10:11], off offset:1024
	v_pk_mul_f32 v[52:53], v[60:61], v[56:57] op_sel_hi:[0,1]
	v_pk_mul_f32 v[32:33], v[60:61], v[32:33] op_sel_hi:[0,1]
	s_waitcnt vmcnt(0)
	v_pk_mul_f32 v[24:25], v[24:25], v[50:51]
	v_pk_mul_f32 v[26:27], v[26:27], v[52:53]
	v_cvt_pk_bf16_f32 v24, v24, v25
	v_cvt_pk_bf16_f32 v25, v26, v27
	global_store_dwordx2 v[28:29], v[24:25], off offset:512
	global_load_dwordx4 v[24:27], v[10:11], off offset:2048
	v_mov_b32_e32 v50, v58
	v_mov_b32_e32 v51, v30
	v_mov_b32_e32 v30, v59
	v_pk_mul_f32 v[50:51], v[60:61], v[50:51] op_sel_hi:[0,1]
	v_pk_mul_f32 v[30:31], v[60:61], v[30:31] op_sel_hi:[0,1]
	s_waitcnt vmcnt(0)
	v_pk_mul_f32 v[24:25], v[24:25], v[50:51]
	v_pk_mul_f32 v[26:27], v[26:27], v[30:31]
	v_cvt_pk_bf16_f32 v24, v24, v25
	v_cvt_pk_bf16_f32 v25, v26, v27
	global_store_dwordx2 v[28:29], v[24:25], off offset:1024
	global_load_dwordx4 v[24:27], v[10:11], off offset:3072
	v_pk_mul_f32 v[30:31], v[60:61], v[62:63] op_sel_hi:[0,1]
	s_waitcnt vmcnt(0)
	v_pk_mul_f32 v[24:25], v[30:31], v[24:25]
	v_pk_mul_f32 v[26:27], v[32:33], v[26:27]
	v_cvt_pk_bf16_f32 v24, v24, v25
	v_cvt_pk_bf16_f32 v25, v26, v27
	global_store_dwordx2 v[28:29], v[24:25], off offset:1536
	global_load_dwordx4 v[24:27], v[12:13], off
	v_pk_mul_f32 v[30:31], v[60:61], v[66:67] op_sel_hi:[0,1]
	v_pk_mul_f32 v[32:33], v[60:61], v[34:35] op_sel_hi:[0,1]
	s_waitcnt vmcnt(0)
	v_pk_mul_f32 v[24:25], v[30:31], v[24:25]
	v_pk_mul_f32 v[26:27], v[32:33], v[26:27]
	v_cvt_pk_bf16_f32 v24, v24, v25
	v_cvt_pk_bf16_f32 v25, v26, v27
	global_store_dwordx2 v[28:29], v[24:25], off offset:2048
	global_load_dwordx4 v[24:27], v[14:15], off
	v_pk_mul_f32 v[30:31], v[60:61], v[68:69] op_sel_hi:[0,1]
	v_pk_mul_f32 v[32:33], v[60:61], v[36:37] op_sel_hi:[0,1]
	s_waitcnt vmcnt(0)
	v_pk_mul_f32 v[24:25], v[30:31], v[24:25]
	v_pk_mul_f32 v[26:27], v[32:33], v[26:27]
	v_cvt_pk_bf16_f32 v24, v24, v25
	v_cvt_pk_bf16_f32 v25, v26, v27
	global_store_dwordx2 v[28:29], v[24:25], off offset:2560
	global_load_dwordx4 v[24:27], v[16:17], off
	v_pk_mul_f32 v[30:31], v[60:61], v[74:75] op_sel_hi:[0,1]
	v_pk_mul_f32 v[32:33], v[60:61], v[38:39] op_sel_hi:[0,1]
	s_waitcnt vmcnt(0)
	v_pk_mul_f32 v[24:25], v[30:31], v[24:25]
	v_pk_mul_f32 v[26:27], v[32:33], v[26:27]
	v_cvt_pk_bf16_f32 v24, v24, v25
	v_cvt_pk_bf16_f32 v25, v26, v27
	global_store_dwordx2 v[28:29], v[24:25], off offset:3072
	global_load_dwordx4 v[24:27], v[18:19], off
	v_pk_mul_f32 v[30:31], v[60:61], v[80:81] op_sel_hi:[0,1]
	v_pk_mul_f32 v[32:33], v[60:61], v[40:41] op_sel_hi:[0,1]
	s_waitcnt vmcnt(0)
	v_pk_mul_f32 v[24:25], v[30:31], v[24:25]
	v_pk_mul_f32 v[26:27], v[32:33], v[26:27]
	v_cvt_pk_bf16_f32 v24, v24, v25
	v_cvt_pk_bf16_f32 v25, v26, v27
	global_store_dwordx2 v[28:29], v[24:25], off offset:3584
	s_branch .LBB0_206

; #define GAS __attribute__((address_space(1)))
; __device__ __forceinline__ unsigned pk2(float lo, float hi) { f32x2_t v = {lo, hi}; bf16x2_t b = __builtin_convertvector(v, bf16x2_t); return __builtin_bit_cast(unsigned, b); }
; __device__ __forceinline__ float bflo(unsigned u) { return __uint_as_float(u << 16); }
; __device__ __forceinline__ float bfhi(unsigned u) { return __uint_as_float(u & 0xffff0000u); }
; __device__ __forceinline__ void rows_latent(const Ctx& C, const bf16* CQKV, const float* qn, const float* kvn, const int* pos, bf16* CQN, bf16* CKVN, bf16* KR, float* COSt, float* SINt) {
;     ...
;     for (int m = gw; m < T; m += NGW) {
;         const bf16* rowp = CQKV + (size_t)m * 1280;
; #pragma unroll
;         for (int part = 0; part < 2; ++part) {
;             const GAS v4u* p = (const GAS v4u*)(rowp + part * 512) + C.lane; const v4u w = *p;
;             float f[8] = {bflo(w.x), bfhi(w.x), bflo(w.y), bfhi(w.y), bflo(w.z), bfhi(w.z), bflo(w.w), bfhi(w.w)}; float s = 0.f;
; #pragma unroll
;             for (int e = 0; e < 8; ++e) s += f[e] * f[e];
;             const float rstd = 1.0f / sqrtf(wave_sum(s) * (1.0f / 512.0f) + EPS);
;             const float* nw = (part == 0 ? qn : kvn) + 8 * C.lane; const f32x4 n0 = *(const GAS f32x4*)nw, n1 = *(const GAS f32x4*)(nw + 4);
;             v4u o; o.x = pk2(f[0] * rstd * n0.x, f[1] * rstd * n0.y); o.y = pk2(f[2] * rstd * n0.z, f[3] * rstd * n0.w); o.z = pk2(f[4] * rstd * n1.x, f[5] * rstd * n1.y); o.w = pk2(f[6] * rstd * n1.z, f[7] * rstd * n1.w);
;             *((GAS v4u*)((part == 0 ? CQN : CKVN) + (size_t)m * 512) + C.lane) = o;
;         }
.LBB0_339:
	v_lshl_add_u64 v[36:37], s[90:91], 0, v[14:15]
	global_load_dwordx4 v[24:27], v[36:37], off offset:-1024
	global_load_dwordx4 v[28:31], v[2:3], off offset:16
	global_load_dwordx4 v[32:35], v[2:3], off
	s_waitcnt vmcnt(2)
	v_lshlrev_b32_e32 v42, 16, v24
	v_and_b32_e32 v43, 0xffff0000, v24
	v_lshlrev_b32_e32 v38, 16, v27
	v_and_b32_e32 v39, 0xffff0000, v27
	v_lshlrev_b32_e32 v40, 16, v26
	v_and_b32_e32 v41, 0xffff0000, v26
	v_lshlrev_b32_e32 v26, 16, v25
	v_and_b32_e32 v27, 0xffff0000, v25
	v_pk_mul_f32 v[48:49], v[42:43], v[42:43]
	v_pk_mul_f32 v[46:47], v[26:27], v[26:27]
	v_add_f32_e32 v48, v48, v49
	v_add_f32_e32 v46, v46, v48
	v_pk_mul_f32 v[44:45], v[40:41], v[40:41]
	v_add_f32_e32 v46, v47, v46
	v_add_f32_e32 v44, v44, v46
	v_pk_mul_f32 v[24:25], v[38:39], v[38:39]
	v_add_f32_e32 v44, v45, v44
	v_add_f32_e32 v24, v24, v44
	v_add_f32_e32 v24, v25, v24
	s_nop 1
	v_add_f32_dpp v24, v24, v24 quad_perm:[1,0,3,2] row_mask:0xf bank_mask:0xf
	v_lshl_add_u64 v[44:45], s[90:91], 0, v[10:11]
	s_nop 1
	v_add_f32_dpp v24, v24, v24 quad_perm:[2,3,0,1] row_mask:0xf bank_mask:0xf
	s_nop 1
	v_add_f32_dpp v24, v24, v24 row_half_mirror row_mask:0xf bank_mask:0xf
	s_nop 1
	v_add_f32_dpp v24, v24, v24 row_mirror row_mask:0xf bank_mask:0xf
	ds_bpermute_b32 v25, v21, v24
	s_waitcnt lgkmcnt(0)
	v_add_f32_e32 v24, v24, v25
	v_mov_b32_e32 v25, v24
	s_nop 1
	v_permlane32_swap_b32_e32 v25, v24
	v_add_f32_e32 v24, v24, v25
	v_fmamk_f32 v24, v24, 0x3b000000, v0
	v_mul_f32_e32 v25, 0x4f800000, v24
	v_cmp_gt_f32_e32 vcc, s3, v24
	s_nop 1
	v_cndmask_b32_e32 v24, v24, v25, vcc
	v_sqrt_f32_e32 v25, v24
	s_nop 0
	v_add_u32_e32 v46, -1, v25
	v_add_u32_e32 v47, 1, v25
	v_fma_f32 v48, -v46, v25, v24
	v_fma_f32 v49, -v47, v25, v24
	v_cmp_ge_f32_e64 s[6:7], 0, v48
	s_nop 1
	v_cndmask_b32_e64 v25, v25, v46, s[6:7]
	v_cmp_lt_f32_e64 s[6:7], 0, v49
	s_nop 1
	v_cndmask_b32_e64 v25, v25, v47, s[6:7]
	v_mul_f32_e32 v46, 0x37800000, v25
	v_cndmask_b32_e32 v25, v25, v46, vcc
	v_cmp_class_f32_e32 vcc, v24, v23
	s_nop 1
	v_cndmask_b32_e32 v24, v25, v24, vcc
	v_div_scale_f32 v25, s[6:7], v24, v24, 1.0
	v_rcp_f32_e32 v48, v25
	v_add_co_u32_e32 v46, vcc, s28, v44
	v_fma_f32 v50, -v25, v48, 1.0
	s_nop 0
	v_addc_co_u32_e32 v47, vcc, 0, v45, vcc
	v_div_scale_f32 v49, vcc, 1.0, v24, 1.0
	v_fmac_f32_e32 v48, v50, v48
	v_mul_f32_e32 v50, v49, v48
	v_fma_f32 v51, -v25, v50, v49
	v_fmac_f32_e32 v50, v51, v48
	v_fma_f32 v25, -v25, v50, v49
	v_div_fmas_f32 v25, v25, v48, v50
	v_div_fixup_f32 v24, v25, v24, 1.0
	v_pk_mul_f32 v[42:43], v[24:25], v[42:43] op_sel_hi:[0,1]
	v_pk_mul_f32 v[26:27], v[24:25], v[26:27] op_sel_hi:[0,1]
	v_pk_mul_f32 v[40:41], v[24:25], v[40:41] op_sel_hi:[0,1]
	v_pk_mul_f32 v[24:25], v[24:25], v[38:39] op_sel_hi:[0,1]
	s_waitcnt vmcnt(0)
	v_pk_mul_f32 v[32:33], v[32:33], v[42:43]
	v_pk_mul_f32 v[26:27], v[34:35], v[26:27]
	v_pk_mul_f32 v[28:29], v[28:29], v[40:41]
	v_pk_mul_f32 v[30:31], v[30:31], v[24:25]
	v_cvt_pk_bf16_f32 v24, v32, v33
	v_cvt_pk_bf16_f32 v25, v26, v27
	v_cvt_pk_bf16_f32 v26, v28, v29
	v_cvt_pk_bf16_f32 v27, v30, v31
	global_store_dwordx4 v[46:47], v[24:27], off
	global_load_dwordx4 v[24:27], v[36:37], off
	s_nop 0
	global_load_dwordx4 v[28:31], v[4:5], off offset:16
	global_load_dwordx4 v[32:35], v[4:5], off
	s_waitcnt vmcnt(2)
	v_lshlrev_b32_e32 v40, 16, v24
	v_and_b32_e32 v41, 0xffff0000, v24
	v_lshlrev_b32_e32 v36, 16, v27
	v_and_b32_e32 v37, 0xffff0000, v27
	v_lshlrev_b32_e32 v38, 16, v26
	v_and_b32_e32 v39, 0xffff0000, v26
	v_lshlrev_b32_e32 v26, 16, v25
	v_and_b32_e32 v27, 0xffff0000, v25
	v_pk_mul_f32 v[48:49], v[40:41], v[40:41]
	v_pk_mul_f32 v[46:47], v[26:27], v[26:27]
	v_add_f32_e32 v48, v48, v49
	v_add_f32_e32 v46, v46, v48
	v_pk_mul_f32 v[42:43], v[38:39], v[38:39]
	v_add_f32_e32 v46, v47, v46
	v_add_f32_e32 v42, v42, v46
	v_pk_mul_f32 v[24:25], v[36:37], v[36:37]
	v_add_f32_e32 v42, v43, v42
	v_add_f32_e32 v24, v24, v42
	v_add_f32_e32 v24, v25, v24
	s_nop 1
	v_add_f32_dpp v24, v24, v24 quad_perm:[1,0,3,2] row_mask:0xf bank_mask:0xf
	s_nop 1
	v_add_f32_dpp v24, v24, v24 quad_perm:[2,3,0,1] row_mask:0xf bank_mask:0xf
	s_nop 1
	v_add_f32_dpp v24, v24, v24 row_half_mirror row_mask:0xf bank_mask:0xf
	s_nop 1
	v_add_f32_dpp v24, v24, v24 row_mirror row_mask:0xf bank_mask:0xf
	ds_bpermute_b32 v25, v21, v24
	s_waitcnt lgkmcnt(0)
	v_add_f32_e32 v24, v24, v25
	v_mov_b32_e32 v25, v24
	s_nop 1
	v_permlane32_swap_b32_e32 v25, v24
	v_add_f32_e32 v24, v24, v25
	v_fmamk_f32 v24, v24, 0x3b000000, v0
	v_mul_f32_e32 v25, 0x4f800000, v24
	v_cmp_gt_f32_e32 vcc, s3, v24
	s_nop 1
	v_cndmask_b32_e32 v24, v24, v25, vcc
	v_sqrt_f32_e32 v25, v24
	s_nop 0
	v_add_u32_e32 v42, -1, v25
	v_add_u32_e32 v43, 1, v25
	v_fma_f32 v46, -v42, v25, v24
	v_fma_f32 v47, -v43, v25, v24
	v_cmp_ge_f32_e64 s[6:7], 0, v46
	s_nop 1
	v_cndmask_b32_e64 v25, v25, v42, s[6:7]
	v_cmp_lt_f32_e64 s[6:7], 0, v47
	s_nop 1
	v_cndmask_b32_e64 v25, v25, v43, s[6:7]
	v_mul_f32_e32 v42, 0x37800000, v25
	v_cndmask_b32_e32 v25, v25, v42, vcc
	v_cmp_class_f32_e32 vcc, v24, v23
	s_nop 1
	v_cndmask_b32_e32 v24, v25, v24, vcc
	v_div_scale_f32 v25, s[6:7], v24, v24, 1.0
	v_rcp_f32_e32 v42, v25
	v_div_scale_f32 v43, vcc, 1.0, v24, 1.0
	v_fma_f32 v46, -v25, v42, 1.0
	v_fmac_f32_e32 v42, v46, v42
	v_mul_f32_e32 v46, v43, v42
	v_fma_f32 v47, -v25, v46, v43
	v_fmac_f32_e32 v46, v47, v42
	v_fma_f32 v25, -v25, v46, v43
	v_div_fmas_f32 v25, v25, v42, v46
	v_div_fixup_f32 v24, v25, v24, 1.0
	v_pk_mul_f32 v[40:41], v[24:25], v[40:41] op_sel_hi:[0,1]
	v_pk_mul_f32 v[26:27], v[24:25], v[26:27] op_sel_hi:[0,1]
	v_pk_mul_f32 v[38:39], v[24:25], v[38:39] op_sel_hi:[0,1]
	v_pk_mul_f32 v[24:25], v[24:25], v[36:37] op_sel_hi:[0,1]
	v_add_co_u32_e32 v42, vcc, 0x21100000, v44
	s_waitcnt vmcnt(0)
	v_pk_mul_f32 v[32:33], v[32:33], v[40:41]
	v_pk_mul_f32 v[26:27], v[34:35], v[26:27]
	v_pk_mul_f32 v[28:29], v[28:29], v[38:39]
	v_pk_mul_f32 v[30:31], v[30:31], v[24:25]
	v_cvt_pk_bf16_f32 v24, v32, v33
	v_cvt_pk_bf16_f32 v25, v26, v27
	v_cvt_pk_bf16_f32 v26, v28, v29
	v_cvt_pk_bf16_f32 v27, v30, v31
	v_addc_co_u32_e32 v43, vcc, 0, v45, vcc
	global_store_dwordx4 v[42:43], v[24:27], off
	s_and_saveexec_b64 s[6:7], s[4:5]
	s_cbranch_execz .LBB0_338
; __device__ __forceinline__ unsigned f2bf(float f) { unsigned u = __builtin_bit_cast(unsigned, f); return (u + 0x7fffu + ((u >> 16) & 1u)) >> 16; }
; __device__ __forceinline__ float bf2f(bf16 b) { return __uint_as_float(((unsigned)b) << 16); }
; __device__ __forceinline__ void rows_latent(const Ctx& C, const bf16* CQKV, const float* qn, const float* kvn, const int* pos, bf16* CQN, bf16* CKVN, bf16* KR, float* COSt, float* SINt) {
;     ...
;         if (C.lane < 32) {
;             const float ang = (float)pos[m] * invf;
;             const double turns = (double)ang * 0.15915494309189535; const float fr = (float)(turns - __builtin_rint(turns));
;             const float cs = __builtin_amdgcn_cosf(fr), sn = __builtin_amdgcn_sinf(fr);
;             const float a = bf2f(rowp[1024 + C.lane]), b = bf2f(rowp[1056 + C.lane]);
;             KR[(size_t)m * 64 + C.lane] = (bf16)f2bf(a * cs - b * sn); KR[(size_t)m * 64 + 32 + C.lane] = (bf16)f2bf(a * sn + b * cs);
;             COSt[(size_t)m * 32 + C.lane] = cs; SINt[(size_t)m * 32 + C.lane] = sn;
;         }
	global_load_dword v30, v1, s[0:1]
	v_lshl_add_u64 v[24:25], s[90:91], 0, v[12:13]
	v_add_co_u32_e32 v24, vcc, 0xe100000, v24
	v_lshl_add_u64 v[26:27], s[90:91], 0, v[6:7]
	s_nop 0
	v_addc_co_u32_e32 v25, vcc, 0, v25, vcc
	global_load_ushort v34, v[24:25], off offset:2048
	global_load_ushort v35, v[24:25], off offset:2112
	v_lshl_add_u64 v[24:25], s[90:91], 0, v[8:9]
	v_add_co_u32_e32 v24, vcc, 0x600000, v24
	s_waitcnt vmcnt(2)
	v_cvt_f32_i32_e32 v30, v30
	v_addc_co_u32_e32 v25, vcc, 0, v25, vcc
	v_add_co_u32_e32 v28, vcc, 0x200000, v26
	v_mul_f32_e32 v30, v16, v30
	v_cvt_f64_f32_e32 v[30:31], v30
	v_mul_f64 v[32:33], v[30:31], s[26:27]
	v_rndne_f64_e32 v[32:33], v[32:33]
	v_fma_f64 v[30:31], v[30:31], s[26:27], -v[32:33]
	v_cvt_f32_f64_e32 v30, v[30:31]
	v_sin_f32_e32 v31, v30
	v_cos_f32_e32 v30, v30
	s_waitcnt vmcnt(0)
	v_lshlrev_b32_e32 v33, 16, v35
	v_addc_co_u32_e32 v29, vcc, 0, v27, vcc
	v_lshlrev_b32_e32 v32, 16, v34
	v_mul_f32_e32 v34, v31, v33
	v_mul_f32_e32 v33, v30, v33
	global_store_dword v[28:29], v30, off
	v_fma_f32 v28, v30, v32, -v34
	v_fmac_f32_e32 v33, v31, v32
	v_bfe_u32 v29, v28, 16, 1
	v_add_co_u32_e32 v26, vcc, 0x400000, v26
	v_bfe_u32 v30, v33, 16, 1
	v_add3_u32 v28, v28, v29, s29
	v_addc_co_u32_e32 v27, vcc, 0, v27, vcc
	v_add3_u32 v29, v33, v30, s29
	global_store_short_d16_hi v[24:25], v28, off
	global_store_short_d16_hi v[24:25], v29, off offset:64
	global_store_dword v[26:27], v31, off
	s_branch .LBB0_338

; #define GAS __attribute__((address_space(1)))
; __device__ __forceinline__ float bflo(unsigned u) { return __uint_as_float(u << 16); }
; __device__ __forceinline__ float bfhi(unsigned u) { return __uint_as_float(u & 0xffff0000u); }
; template <bool XIN_BF, bool XOUT_BF>
; __device__ __forceinline__ void rows_update_g(const Ctx& C, const float* xin, const bf16* xin_bf, const bf16* Y, const float* wpost, float scale, float* xout, bf16* xout_bf, const float* wpre, bf16* HN) {
;     ...
;     for (int m = gw; m < T; m += NGW) {
;         const GAS v2u* yr = (const GAS v2u*)(Y + (size_t)m * D) + C.lane;
;         f32x4 v[8]; float s = 0.f;
; #pragma unroll
;         for (int j = 0; j < 8; ++j) { const v2u w = yr[64 * j]; v[j] = (f32x4){bflo(w.x), bfhi(w.x), bflo(w.y), bfhi(w.y)}; s += (v[j].x * v[j].x + v[j].y * v[j].y) + (v[j].z * v[j].z + v[j].w * v[j].w); }
;         const float rstd = scale / sqrtf(wave_sum(s) * (1.0f / D) + EPS);
;         float s2 = 0.f;
; #pragma unroll
;         for (int j = 0; j < 8; ++j) { const f32x4 ww = *((const GAS f32x4*)wpost + C.lane + 64 * j); f32x4 xv;
;             if (XIN_BF) { const v2u xw = *((const GAS v2u*)(xin_bf + (size_t)m * D) + C.lane + 64 * j); xv = (f32x4){bflo(xw.x), bfhi(xw.x), bflo(xw.y), bfhi(xw.y)}; }
;             else xv = *((const GAS f32x4*)(xin + (size_t)m * D) + C.lane + 64 * j);
;             v[j] = xv + v[j] * rstd * ww;
.LBB0_1075:
	v_lshl_add_u64 v[22:23], s[0:1], 0, v[0:1]
	v_add_co_u32_e32 v24, vcc, 0xa100000, v22
	s_nop 1
	v_addc_co_u32_e32 v25, vcc, 0, v23, vcc
	global_load_dwordx2 v[26:27], v[24:25], off
	global_load_dwordx2 v[28:29], v[24:25], off offset:512
	global_load_dwordx2 v[30:31], v[24:25], off offset:1024
	global_load_dwordx2 v[32:33], v[24:25], off offset:1536
	global_load_dwordx2 v[34:35], v[24:25], off offset:2048
	global_load_dwordx2 v[36:37], v[24:25], off offset:2560
	global_load_dwordx2 v[40:41], v[24:25], off offset:3072
	global_load_dwordx2 v[46:47], v[24:25], off offset:3584
	global_load_dwordx4 v[42:45], v[2:3], off
	v_lshl_add_u64 v[24:25], s[10:11], 0, v[0:1]
	global_load_dwordx2 v[48:49], v[24:25], off
	s_waitcnt vmcnt(9)
	v_and_b32_e32 v51, 0xffff0000, v26
	v_and_b32_e32 v61, 0xffff0000, v27
	v_lshlrev_b32_e32 v50, 16, v26
	v_lshlrev_b32_e32 v60, 16, v27
	s_waitcnt vmcnt(8)
	v_lshlrev_b32_e32 v63, 16, v29
	v_lshlrev_b32_e32 v62, 16, v28
	v_and_b32_e32 v65, 0xffff0000, v29
	v_and_b32_e32 v64, 0xffff0000, v28
	s_waitcnt vmcnt(7)
	v_lshlrev_b32_e32 v66, 16, v30
	v_and_b32_e32 v67, 0xffff0000, v30
	v_lshlrev_b32_e32 v68, 16, v31
	v_and_b32_e32 v69, 0xffff0000, v31
	s_waitcnt vmcnt(6)
	v_lshlrev_b32_e32 v71, 16, v32
	s_waitcnt vmcnt(2)
	v_lshlrev_b32_e32 v31, 16, v46
	v_and_b32_e32 v29, 0xffff0000, v46
	v_mul_f32_e32 v28, v61, v61
	v_mul_f32_e32 v30, v51, v51
	v_and_b32_e32 v73, 0xffff0000, v32
	v_lshlrev_b32_e32 v74, 16, v33
	v_and_b32_e32 v75, 0xffff0000, v33
	v_lshlrev_b32_e32 v77, 16, v35
	v_lshlrev_b32_e32 v76, 16, v34
	v_and_b32_e32 v79, 0xffff0000, v35
	v_and_b32_e32 v78, 0xffff0000, v34
	v_lshlrev_b32_e32 v32, 16, v40
	v_and_b32_e32 v33, 0xffff0000, v40
	v_lshlrev_b32_e32 v34, 16, v41
	v_and_b32_e32 v35, 0xffff0000, v41
	v_lshlrev_b32_e32 v26, 16, v47
	v_and_b32_e32 v27, 0xffff0000, v47
	v_pk_mul_f32 v[40:41], v[64:65], v[64:65]
	v_mov_b32_e32 v47, v71
	v_mul_f32_e32 v46, v67, v67
	v_mul_f32_e32 v70, v69, v69
	v_pk_fma_f32 v[86:87], v[60:61], v[60:61], v[28:29] op_sel_hi:[1,1,0]
	v_pk_fma_f32 v[88:89], v[50:51], v[50:51], v[30:31] op_sel_hi:[1,1,0]
	v_pk_fma_f32 v[40:41], v[62:63], v[62:63], v[40:41]
	v_pk_fma_f32 v[90:91], v[66:67], v[66:67], v[46:47] op_sel_hi:[1,1,0]
	v_pk_fma_f32 v[92:93], v[68:69], v[68:69], v[70:71] op_sel_hi:[1,1,0]
	v_mov_b32_e32 v70, v88
	v_mov_b32_e32 v46, v86
	v_mul_f32_e32 v84, v73, v73
	v_mul_f32_e32 v96, v74, v74
	v_mul_f32_e32 v97, v75, v75
	v_pk_add_f32 v[86:87], v[88:89], v[86:87]
	v_pk_add_f32 v[40:41], v[40:41], v[40:41] op_sel:[0,1] op_sel_hi:[1,0]
	v_pk_mul_f32 v[46:47], v[70:71], v[46:47]
	v_mov_b32_e32 v91, v96
	v_mov_b32_e32 v93, v97
	v_mov_b32_e32 v41, v84
	v_mov_b32_e32 v87, v47
	v_pk_mul_f32 v[80:81], v[78:79], v[78:79]
	v_pk_add_f32 v[88:89], v[90:91], v[92:93]
	v_pk_add_f32 v[40:41], v[86:87], v[40:41]
	v_pk_fma_f32 v[80:81], v[76:77], v[76:77], v[80:81]
	v_pk_add_f32 v[40:41], v[40:41], v[88:89]
	v_lshlrev_b32_e32 v39, 16, v37
	v_lshlrev_b32_e32 v38, 16, v36
	v_and_b32_e32 v37, 0xffff0000, v37
	v_and_b32_e32 v36, 0xffff0000, v36
	v_pk_add_f32 v[80:81], v[80:81], v[80:81] op_sel:[0,1] op_sel_hi:[1,0]
	v_pk_add_f32 v[40:41], v[40:41], v[40:41] op_sel:[0,1] op_sel_hi:[1,0]
	v_pk_mul_f32 v[82:83], v[36:37], v[36:37]
	v_mov_b32_e32 v85, v31
	v_mov_b32_e32 v84, v80
	v_mov_b32_e32 v30, v40
	v_mul_f32_e32 v72, v33, v33
	v_pk_fma_f32 v[82:83], v[38:39], v[38:39], v[82:83]
	v_pk_add_f32 v[40:41], v[40:41], v[80:81]
	v_pk_mul_f32 v[46:47], v[30:31], v[84:85]
	v_mul_f32_e32 v28, v35, v35
	v_mul_f32_e32 v98, v29, v29
	v_mul_f32_e32 v99, v26, v26
	v_mul_f32_e32 v100, v27, v27
	v_pk_fma_f32 v[94:95], v[32:33], v[32:33], v[72:73] op_sel_hi:[1,1,0]
	v_pk_add_f32 v[82:83], v[82:83], v[82:83] op_sel:[0,1] op_sel_hi:[1,0]
	v_mov_b32_e32 v41, v47
	v_pk_fma_f32 v[46:47], v[34:35], v[34:35], v[28:29] op_sel_hi:[1,1,0]
	v_mov_b32_e32 v95, v99
	v_mov_b32_e32 v83, v98
	v_mov_b32_e32 v47, v100
	v_pk_add_f32 v[40:41], v[40:41], v[82:83]
	v_pk_add_f32 v[46:47], v[94:95], v[46:47]
	s_nop 0
	v_pk_add_f32 v[40:41], v[40:41], v[46:47]
	s_waitcnt vmcnt(0)
	v_lshlrev_b32_e32 v46, 16, v48
	v_add_f32_e32 v28, v40, v41
	ds_bpermute_b32 v30, v52, v28
	v_add_co_u32_e32 v40, vcc, s12, v22
	v_and_b32_e32 v47, 0xffff0000, v48
	s_nop 0
	v_addc_co_u32_e32 v41, vcc, 0, v23, vcc
	s_waitcnt lgkmcnt(0)
	v_add_f32_e32 v28, v28, v30
	ds_bpermute_b32 v30, v53, v28
	v_lshlrev_b32_e32 v48, 16, v49
	v_and_b32_e32 v49, 0xffff0000, v49
	s_waitcnt lgkmcnt(0)
	v_add_f32_e32 v28, v28, v30
	ds_bpermute_b32 v30, v54, v28
	s_waitcnt lgkmcnt(0)
	v_add_f32_e32 v28, v28, v30
	ds_bpermute_b32 v30, v55, v28
	s_waitcnt lgkmcnt(0)
	v_add_f32_e32 v28, v28, v30
	ds_bpermute_b32 v30, v56, v28
	s_waitcnt lgkmcnt(0)
	v_add_f32_e32 v28, v28, v30
	ds_bpermute_b32 v30, v57, v28
	s_waitcnt lgkmcnt(0)
; #define GAS __attribute__((address_space(1)))
; __device__ __forceinline__ unsigned pk2(float lo, float hi) { f32x2_t v = {lo, hi}; bf16x2_t b = __builtin_convertvector(v, bf16x2_t); return __builtin_bit_cast(unsigned, b); }
; __device__ __forceinline__ float bflo(unsigned u) { return __uint_as_float(u << 16); }
; __device__ __forceinline__ float bfhi(unsigned u) { return __uint_as_float(u & 0xffff0000u); }
; template <bool XIN_BF, bool XOUT_BF>
; __device__ __forceinline__ void rows_update_g(const Ctx& C, const float* xin, const bf16* xin_bf, const bf16* Y, const float* wpost, float scale, float* xout, bf16* xout_bf, const float* wpre, bf16* HN) {
;     ...
;         const float rstd = scale / sqrtf(wave_sum(s) * (1.0f / D) + EPS);
;         float s2 = 0.f;
; #pragma unroll
;         for (int j = 0; j < 8; ++j) { const f32x4 ww = *((const GAS f32x4*)wpost + C.lane + 64 * j); f32x4 xv;
;             if (XIN_BF) { const v2u xw = *((const GAS v2u*)(xin_bf + (size_t)m * D) + C.lane + 64 * j); xv = (f32x4){bflo(xw.x), bfhi(xw.x), bflo(xw.y), bfhi(xw.y)}; }
;             else xv = *((const GAS f32x4*)(xin + (size_t)m * D) + C.lane + 64 * j);
;             v[j] = xv + v[j] * rstd * ww;
;             if (XOUT_BF) { const v2u ow = (v2u){pk2(v[j].x, v[j].y), pk2(v[j].z, v[j].w)}; *((GAS v2u*)(xout_bf + (size_t)m * D) + C.lane + 64 * j) = ow;
;                 v[j] = (f32x4){bflo(ow.x), bfhi(ow.x), bflo(ow.y), bfhi(ow.y)}; }
;             else *((GAS f32x4*)(xout + (size_t)m * D) + C.lane + 64 * j) = v[j];
	v_add_f32_e32 v28, v28, v30
	v_fmamk_f32 v28, v28, 0x3a000000, v58
	v_mul_f32_e32 v30, 0x4f800000, v28
	v_cmp_gt_f32_e32 vcc, s3, v28
	s_nop 1
	v_cndmask_b32_e32 v28, v28, v30, vcc
	v_sqrt_f32_e32 v30, v28
	s_nop 0
	v_add_u32_e32 v70, -1, v30
	v_add_u32_e32 v72, 1, v30
	v_fma_f32 v80, -v70, v30, v28
	v_fma_f32 v81, -v72, v30, v28
	v_cmp_ge_f32_e64 s[6:7], 0, v80
	s_nop 1
	v_cndmask_b32_e64 v30, v30, v70, s[6:7]
	v_cmp_lt_f32_e64 s[6:7], 0, v81
	s_nop 1
	v_cndmask_b32_e64 v30, v30, v72, s[6:7]
	v_mul_f32_e32 v70, 0x37800000, v30
	v_cndmask_b32_e32 v30, v30, v70, vcc
	v_cmp_class_f32_e32 vcc, v28, v59
	s_nop 1
	v_cndmask_b32_e32 v28, v30, v28, vcc
	v_div_scale_f32 v30, s[6:7], v28, v28, 1.0
	v_rcp_f32_e32 v70, v30
	v_div_scale_f32 v72, vcc, 1.0, v28, 1.0
	v_fma_f32 v80, -v30, v70, 1.0
	v_fmac_f32_e32 v70, v80, v70
	v_mul_f32_e32 v80, v72, v70
	v_fma_f32 v81, -v30, v80, v72
	v_fmac_f32_e32 v80, v81, v70
	v_fma_f32 v30, -v30, v80, v72
	v_div_fmas_f32 v30, v30, v70, v80
	v_div_fixup_f32 v30, v30, v28, 1.0
	v_pk_mul_f32 v[50:51], v[30:31], v[50:51] op_sel_hi:[0,1]
	v_pk_mul_f32 v[60:61], v[30:31], v[60:61] op_sel_hi:[0,1]
	v_pk_fma_f32 v[44:45], v[44:45], v[60:61], v[48:49]
	v_pk_fma_f32 v[42:43], v[42:43], v[50:51], v[46:47]
	v_mov_b32_e32 v50, v62
	v_cvt_pk_bf16_f32 v42, v42, v43
	v_cvt_pk_bf16_f32 v43, v44, v45
	global_store_dwordx2 v[40:41], v[42:43], off
	global_load_dwordx2 v[48:49], v[24:25], off offset:512
	global_load_dwordx4 v[44:47], v[2:3], off offset:1024
	v_mov_b32_e32 v51, v64
	v_mov_b32_e32 v64, v63
	v_pk_mul_f32 v[50:51], v[30:31], v[50:51] op_sel_hi:[0,1]
	v_pk_mul_f32 v[60:61], v[30:31], v[64:65] op_sel_hi:[0,1]
	v_mov_b32_e32 v72, v71
	v_pk_mul_f32 v[32:33], v[30:31], v[32:33] op_sel_hi:[0,1]
	v_pk_mul_f32 v[34:35], v[30:31], v[34:35] op_sel_hi:[0,1]
	v_mov_b32_e32 v28, v31
	v_pk_mul_f32 v[26:27], v[26:27], v[30:31] op_sel_hi:[1,0]
	s_and_b64 vcc, exec, s[4:5]
	s_waitcnt vmcnt(1)
	v_lshlrev_b32_e32 v62, 16, v48
	v_and_b32_e32 v63, 0xffff0000, v48
	v_lshlrev_b32_e32 v48, 16, v49
	v_and_b32_e32 v49, 0xffff0000, v49
	s_waitcnt vmcnt(0)
	v_pk_fma_f32 v[46:47], v[46:47], v[60:61], v[48:49]
	v_pk_fma_f32 v[44:45], v[44:45], v[50:51], v[62:63]
	v_pk_mul_f32 v[60:61], v[30:31], v[66:67] op_sel_hi:[0,1]
	v_cvt_pk_bf16_f32 v44, v44, v45
	v_cvt_pk_bf16_f32 v45, v46, v47
	global_store_dwordx2 v[40:41], v[44:45], off offset:512
	global_load_dwordx2 v[50:51], v[24:25], off offset:1024
	global_load_dwordx4 v[46:49], v[2:3], off offset:2048
	v_pk_mul_f32 v[62:63], v[30:31], v[68:69] op_sel_hi:[0,1]
	s_waitcnt vmcnt(1)
	v_lshlrev_b32_e32 v64, 16, v50
	v_and_b32_e32 v65, 0xffff0000, v50
	v_lshlrev_b32_e32 v50, 16, v51
	v_and_b32_e32 v51, 0xffff0000, v51
	s_waitcnt vmcnt(0)
	v_pk_fma_f32 v[48:49], v[48:49], v[62:63], v[50:51]
	v_pk_fma_f32 v[46:47], v[46:47], v[60:61], v[64:65]
	v_pk_mul_f32 v[62:63], v[72:73], v[30:31] op_sel_hi:[1,0]
	v_cvt_pk_bf16_f32 v46, v46, v47
	v_cvt_pk_bf16_f32 v47, v48, v49
	global_store_dwordx2 v[40:41], v[46:47], off offset:1024
	global_load_dwordx2 v[60:61], v[24:25], off offset:1536
	global_load_dwordx4 v[48:51], v[2:3], off offset:3072
	v_pk_mul_f32 v[64:65], v[74:75], v[30:31] op_sel_hi:[1,0]
	s_waitcnt vmcnt(1)
	v_lshlrev_b32_e32 v66, 16, v60
	v_and_b32_e32 v67, 0xffff0000, v60
	v_lshlrev_b32_e32 v60, 16, v61
	v_and_b32_e32 v61, 0xffff0000, v61
	s_waitcnt vmcnt(0)
	v_pk_fma_f32 v[50:51], v[50:51], v[64:65], v[60:61]
	v_pk_fma_f32 v[48:49], v[48:49], v[62:63], v[66:67]
	v_mov_b32_e32 v64, v76
	v_cvt_pk_bf16_f32 v48, v48, v49
	v_cvt_pk_bf16_f32 v49, v50, v51
	global_store_dwordx2 v[40:41], v[48:49], off offset:1536
	global_load_dwordx2 v[50:51], v[24:25], off offset:2048
	global_load_dwordx4 v[60:63], v[4:5], off
	v_mov_b32_e32 v65, v78
	v_mov_b32_e32 v78, v77
	v_pk_mul_f32 v[64:65], v[30:31], v[64:65] op_sel_hi:[0,1]
	v_pk_mul_f32 v[66:67], v[30:31], v[78:79] op_sel_hi:[0,1]
	s_waitcnt vmcnt(1)
	v_lshlrev_b32_e32 v68, 16, v50
	v_and_b32_e32 v69, 0xffff0000, v50
	v_lshlrev_b32_e32 v50, 16, v51
	v_and_b32_e32 v51, 0xffff0000, v51
	s_waitcnt vmcnt(0)
	v_pk_fma_f32 v[62:63], v[62:63], v[66:67], v[50:51]
	v_pk_fma_f32 v[50:51], v[60:61], v[64:65], v[68:69]
	v_mov_b32_e32 v66, v38
	v_cvt_pk_bf16_f32 v50, v50, v51
	v_cvt_pk_bf16_f32 v51, v62, v63
	global_store_dwordx2 v[40:41], v[50:51], off offset:2048
	global_load_dwordx2 v[64:65], v[24:25], off offset:2560
	global_load_dwordx4 v[60:63], v[6:7], off
	v_mov_b32_e32 v67, v36
	v_mov_b32_e32 v36, v39
	v_pk_mul_f32 v[38:39], v[30:31], v[66:67] op_sel_hi:[0,1]
	v_pk_mul_f32 v[36:37], v[30:31], v[36:37] op_sel_hi:[0,1]
	s_waitcnt vmcnt(1)
	v_lshlrev_b32_e32 v66, 16, v64
	v_and_b32_e32 v67, 0xffff0000, v64
	v_lshlrev_b32_e32 v64, 16, v65
	v_and_b32_e32 v65, 0xffff0000, v65
	s_waitcnt vmcnt(0)
	v_pk_fma_f32 v[62:63], v[36:37], v[62:63], v[64:65]
	v_pk_fma_f32 v[36:37], v[38:39], v[60:61], v[66:67]
	s_nop 0
	v_cvt_pk_bf16_f32 v36, v36, v37
	v_cvt_pk_bf16_f32 v37, v62, v63
	global_store_dwordx2 v[40:41], v[36:37], off offset:2560
	global_load_dwordx2 v[38:39], v[24:25], off offset:3072
	global_load_dwordx4 v[60:63], v[8:9], off
	s_waitcnt vmcnt(1)
	v_lshlrev_b32_e32 v64, 16, v38
	v_and_b32_e32 v65, 0xffff0000, v38
	v_lshlrev_b32_e32 v38, 16, v39
	v_and_b32_e32 v39, 0xffff0000, v39
	s_waitcnt vmcnt(0)
	v_pk_fma_f32 v[34:35], v[34:35], v[62:63], v[38:39]
	v_pk_fma_f32 v[32:33], v[32:33], v[60:61], v[64:65]
	s_nop 0
	v_cvt_pk_bf16_f32 v32, v32, v33
	v_cvt_pk_bf16_f32 v33, v34, v35
	global_store_dwordx2 v[40:41], v[32:33], off offset:3072
	global_load_dwordx2 v[34:35], v[24:25], off offset:3584
	global_load_dwordx4 v[60:63], v[10:11], off
	v_pk_mul_f32 v[24:25], v[28:29], v[30:31] op_sel_hi:[1,0]
	s_waitcnt vmcnt(1)
	v_lshlrev_b32_e32 v28, 16, v34
	v_and_b32_e32 v29, 0xffff0000, v34
	v_lshlrev_b32_e32 v30, 16, v35
	v_and_b32_e32 v31, 0xffff0000, v35
	s_waitcnt vmcnt(0)
	v_pk_fma_f32 v[26:27], v[26:27], v[62:63], v[30:31]
	v_pk_fma_f32 v[24:25], v[24:25], v[60:61], v[28:29]
	s_nop 0
	v_cvt_pk_bf16_f32 v24, v24, v25
	v_cvt_pk_bf16_f32 v25, v26, v27
	global_store_dwordx2 v[40:41], v[24:25], off offset:3584
	s_cbranch_vccnz .LBB0_1074
; template <bool XIN_BF, bool XOUT_BF>
; __device__ __forceinline__ void rows_update_g(const Ctx& C, const float* xin, const bf16* xin_bf, const bf16* Y, const float* wpost, float scale, float* xout, bf16* xout_bf, const float* wpre, bf16* HN) {
;     ...
;             s2 += (v[j].x * v[j].x + v[j].y * v[j].y) + (v[j].z * v[j].z + v[j].w * v[j].w); }
;         if (wpre) { const float r2 = 1.0f / sqrtf(wave_sum(s2) * (1.0f / D) + EPS);
	v_and_b32_e32 v39, 0xffff0000, v45
	v_and_b32_e32 v38, 0xffff0000, v44
	v_lshlrev_b32_e32 v35, 16, v45
	v_lshlrev_b32_e32 v34, 16, v44
	v_pk_mul_f32 v[26:27], v[38:39], v[38:39]
	v_lshlrev_b32_e32 v28, 16, v42
	v_and_b32_e32 v29, 0xffff0000, v42
	v_pk_fma_f32 v[26:27], v[34:35], v[34:35], v[26:27]
	v_lshlrev_b32_e32 v42, 16, v46
	v_and_b32_e32 v45, 0xffff0000, v46
	v_and_b32_e32 v44, s0, v46
	v_lshlrev_b32_e32 v46, 16, v47
	v_and_b32_e32 v47, 0xffff0000, v47
	v_pk_add_f32 v[40:41], v[26:27], v[26:27] op_sel:[0,1] op_sel_hi:[1,0]
	v_mul_f32_e32 v26, v47, v47
	v_lshlrev_b32_e32 v67, 16, v51
	v_lshlrev_b32_e32 v66, 16, v50
	v_and_b32_e32 v51, 0xffff0000, v51
	v_and_b32_e32 v50, 0xffff0000, v50
	v_pk_fma_f32 v[60:61], v[46:47], v[46:47], v[26:27] op_sel_hi:[1,1,0]
	v_pk_mul_f32 v[26:27], v[50:51], v[50:51]
	v_lshlrev_b32_e32 v71, 16, v37
	v_pk_fma_f32 v[26:27], v[66:67], v[66:67], v[26:27]
	v_lshlrev_b32_e32 v70, 16, v36
	v_and_b32_e32 v37, 0xffff0000, v37
	v_and_b32_e32 v36, 0xffff0000, v36
	v_pk_add_f32 v[68:69], v[26:27], v[26:27] op_sel:[0,1] op_sel_hi:[1,0]
	v_pk_mul_f32 v[26:27], v[36:37], v[36:37]
	v_and_b32_e32 v75, 0xffff0000, v32
	v_pk_fma_f32 v[26:27], v[70:71], v[70:71], v[26:27]
	v_lshlrev_b32_e32 v74, 16, v32
	v_pk_add_f32 v[72:73], v[26:27], v[26:27] op_sel:[0,1] op_sel_hi:[1,0]
	v_mul_f32_e32 v26, v75, v75
	v_lshlrev_b32_e32 v32, 16, v33
	v_and_b32_e32 v33, 0xffff0000, v33
	v_pk_fma_f32 v[76:77], v[74:75], v[74:75], v[26:27] op_sel_hi:[1,1,0]
	v_mul_f32_e32 v26, v33, v33
	v_and_b32_e32 v31, 0xffff0000, v43
	v_pk_fma_f32 v[78:79], v[32:33], v[32:33], v[26:27] op_sel_hi:[1,1,0]
	v_lshlrev_b32_e32 v80, 16, v24
	v_and_b32_e32 v83, 0xffff0000, v24
	v_and_b32_e32 v82, s0, v24
	v_lshlrev_b32_e32 v84, 16, v25
	v_and_b32_e32 v85, 0xffff0000, v25
	global_load_dwordx4 v[24:27], v[12:13], off
	v_lshlrev_b32_e32 v30, 16, v43
	v_and_b32_e32 v65, 0xffff0000, v48
	v_mov_b32_e32 v88, v29
	v_mov_b32_e32 v89, v31
	v_mov_b32_e32 v43, v45
	v_lshlrev_b32_e32 v62, 16, v48
	v_and_b32_e32 v64, s0, v48
	v_mov_b32_e32 v63, v65
	v_mov_b32_e32 v86, v28
	v_mov_b32_e32 v87, v30
	v_pk_mul_f32 v[88:89], v[88:89], v[88:89]
	v_pk_mul_f32 v[44:45], v[44:45], v[44:45]
	v_lshlrev_b32_e32 v48, 16, v49
	v_and_b32_e32 v49, 0xffff0000, v49
	v_pk_fma_f32 v[86:87], v[86:87], v[86:87], v[88:89]
	v_pk_mul_f32 v[64:65], v[64:65], v[64:65]
	v_pk_mov_b32 v[44:45], v[44:45], v[62:63] op_sel:[1,0]
	v_pk_add_f32 v[86:87], v[86:87], v[86:87] op_sel:[0,1] op_sel_hi:[1,0]
	v_pk_mul_f32 v[88:89], v[48:49], v[48:49]
	v_mov_b32_e32 v61, v65
	v_pk_fma_f32 v[64:65], v[42:43], v[42:43], v[44:45]
	v_pk_mul_f32 v[44:45], v[62:63], v[44:45] op_sel_hi:[0,1]
	v_mov_b32_e32 v87, v88
	v_mov_b32_e32 v41, v89
	v_mov_b32_e32 v65, v45
	v_pk_add_f32 v[40:41], v[86:87], v[40:41]
	v_pk_add_f32 v[44:45], v[64:65], v[60:61]
	v_pk_mul_f32 v[60:61], v[82:83], v[82:83]
	v_pk_add_f32 v[40:41], v[44:45], v[40:41]
	v_pk_mul_f32 v[44:45], v[84:85], v[84:85]
	v_pk_add_f32 v[40:41], v[40:41], v[40:41] op_sel:[0,1] op_sel_hi:[1,0]
	v_mov_b32_e32 v77, v44
	v_pk_add_f32 v[40:41], v[40:41], v[68:69]
	v_mov_b32_e32 v79, v45
	v_mov_b32_e32 v73, v61
	v_mul_f32_e32 v41, v80, v80
	v_pk_add_f32 v[44:45], v[76:77], v[78:79]
	v_pk_add_f32 v[40:41], v[40:41], v[72:73]
	v_mov_b32_e32 v81, v83
	v_pk_add_f32 v[40:41], v[40:41], v[44:45]
	s_nop 0
	v_add_f32_e32 v40, v40, v41
	s_nop 1
	v_add_f32_dpp v40, v40, v40 quad_perm:[1,0,3,2] row_mask:0xf bank_mask:0xf
	s_nop 1
	v_add_f32_dpp v40, v40, v40 quad_perm:[2,3,0,1] row_mask:0xf bank_mask:0xf
	s_nop 1
	v_add_f32_dpp v40, v40, v40 row_half_mirror row_mask:0xf bank_mask:0xf
	s_nop 1
	v_add_f32_dpp v40, v40, v40 row_mirror row_mask:0xf bank_mask:0xf
	ds_bpermute_b32 v41, v56, v40
	s_waitcnt lgkmcnt(0)
; #define GAS __attribute__((address_space(1)))
; __device__ __forceinline__ unsigned pk2(float lo, float hi) { f32x2_t v = {lo, hi}; bf16x2_t b = __builtin_convertvector(v, bf16x2_t); return __builtin_bit_cast(unsigned, b); }
; template <bool XIN_BF, bool XOUT_BF>
; __device__ __forceinline__ void rows_update_g(const Ctx& C, const float* xin, const bf16* xin_bf, const bf16* Y, const float* wpost, float scale, float* xout, bf16* xout_bf, const float* wpre, bf16* HN) {
;     ...
;         if (wpre) { const float r2 = 1.0f / sqrtf(wave_sum(s2) * (1.0f / D) + EPS);
;             GAS v2u* o = (GAS v2u*)(HN + (size_t)m * D) + C.lane;
; #pragma unroll
;             for (int j = 0; j < 8; ++j) { const f32x4 ww = *((const GAS f32x4*)wpre + C.lane + 64 * j); o[64 * j] = (v2u){pk2(v[j].x * r2 * ww.x, v[j].y * r2 * ww.y), pk2(v[j].z * r2 * ww.z, v[j].w * r2 * ww.w)}; } }
	v_add_f32_e32 v40, v40, v41
	v_mov_b32_e32 v41, v40
	s_nop 1
	v_permlane32_swap_b32_e32 v41, v40
	v_add_f32_e32 v40, v40, v41
	v_fmamk_f32 v40, v40, 0x3a000000, v58
	v_mul_f32_e32 v41, 0x4f800000, v40
	v_cmp_gt_f32_e32 vcc, s3, v40
	s_nop 1
	v_cndmask_b32_e32 v40, v40, v41, vcc
	v_sqrt_f32_e32 v41, v40
	s_nop 0
	v_add_u32_e32 v44, -1, v41
	v_fma_f32 v45, -v44, v41, v40
	v_cmp_ge_f32_e64 s[6:7], 0, v45
	v_add_u32_e32 v45, 1, v41
	s_nop 0
	v_cndmask_b32_e64 v44, v41, v44, s[6:7]
	v_fma_f32 v41, -v45, v41, v40
	v_cmp_lt_f32_e64 s[6:7], 0, v41
	s_nop 1
	v_cndmask_b32_e64 v41, v44, v45, s[6:7]
	v_mul_f32_e32 v44, 0x37800000, v41
	v_cndmask_b32_e32 v41, v41, v44, vcc
	v_cmp_class_f32_e32 vcc, v40, v59
	s_nop 1
	v_cndmask_b32_e32 v40, v41, v40, vcc
	v_div_scale_f32 v41, s[6:7], v40, v40, 1.0
	v_rcp_f32_e32 v44, v41
	s_nop 0
	v_fma_f32 v45, -v41, v44, 1.0
	v_fmac_f32_e32 v44, v45, v44
	v_div_scale_f32 v45, vcc, 1.0, v40, 1.0
	v_mul_f32_e32 v60, v45, v44
	v_fma_f32 v61, -v41, v60, v45
	v_fmac_f32_e32 v60, v61, v44
	v_fma_f32 v41, -v41, v60, v45
	v_div_fmas_f32 v41, v41, v44, v60
	v_div_fixup_f32 v40, v41, v40, 1.0
	v_pk_mul_f32 v[28:29], v[40:41], v[28:29] op_sel_hi:[0,1]
	s_waitcnt vmcnt(0)
	v_pk_mul_f32 v[24:25], v[24:25], v[28:29]
	v_pk_mul_f32 v[28:29], v[40:41], v[30:31] op_sel_hi:[0,1]
	v_pk_mul_f32 v[26:27], v[26:27], v[28:29]
	v_cvt_pk_bf16_f32 v24, v24, v25
	v_cvt_pk_bf16_f32 v25, v26, v27
	v_add_co_u32_e32 v26, vcc, s13, v22
	v_mov_b32_e32 v28, v34
	s_nop 0
	v_addc_co_u32_e32 v27, vcc, 0, v23, vcc
	global_store_dwordx2 v[26:27], v[24:25], off
	global_load_dwordx4 v[22:25], v[12:13], off offset:1024
	v_mov_b32_e32 v29, v38
	v_mov_b32_e32 v38, v35
	v_pk_mul_f32 v[28:29], v[40:41], v[28:29] op_sel_hi:[0,1]
	v_pk_mul_f32 v[30:31], v[40:41], v[38:39] op_sel_hi:[0,1]
	s_waitcnt vmcnt(0)
	v_pk_mul_f32 v[22:23], v[22:23], v[28:29]
	v_pk_mul_f32 v[24:25], v[24:25], v[30:31]
	v_cvt_pk_bf16_f32 v22, v22, v23
	v_cvt_pk_bf16_f32 v23, v24, v25
	global_store_dwordx2 v[26:27], v[22:23], off offset:512
	global_load_dwordx4 v[22:25], v[12:13], off offset:2048
	v_pk_mul_f32 v[28:29], v[40:41], v[42:43] op_sel_hi:[0,1]
	v_pk_mul_f32 v[30:31], v[40:41], v[46:47] op_sel_hi:[0,1]
	s_waitcnt vmcnt(0)
	v_pk_mul_f32 v[22:23], v[22:23], v[28:29]
	v_pk_mul_f32 v[24:25], v[24:25], v[30:31]
	v_cvt_pk_bf16_f32 v22, v22, v23
	v_cvt_pk_bf16_f32 v23, v24, v25
	global_store_dwordx2 v[26:27], v[22:23], off offset:1024
	global_load_dwordx4 v[22:25], v[12:13], off offset:3072
	v_pk_mul_f32 v[28:29], v[40:41], v[62:63] op_sel_hi:[0,1]
	v_pk_mul_f32 v[30:31], v[40:41], v[48:49] op_sel_hi:[0,1]
	s_waitcnt vmcnt(0)
	v_pk_mul_f32 v[22:23], v[28:29], v[22:23]
	v_pk_mul_f32 v[24:25], v[30:31], v[24:25]
	v_cvt_pk_bf16_f32 v22, v22, v23
	v_cvt_pk_bf16_f32 v23, v24, v25
	global_store_dwordx2 v[26:27], v[22:23], off offset:1536
	global_load_dwordx4 v[22:25], v[14:15], off
	v_mov_b32_e32 v28, v66
	v_mov_b32_e32 v29, v50
	v_mov_b32_e32 v50, v67
	v_pk_mul_f32 v[28:29], v[40:41], v[28:29] op_sel_hi:[0,1]
	v_pk_mul_f32 v[30:31], v[40:41], v[50:51] op_sel_hi:[0,1]
	s_waitcnt vmcnt(0)
	v_pk_mul_f32 v[22:23], v[28:29], v[22:23]
	v_pk_mul_f32 v[24:25], v[30:31], v[24:25]
	v_cvt_pk_bf16_f32 v22, v22, v23
	v_cvt_pk_bf16_f32 v23, v24, v25
	global_store_dwordx2 v[26:27], v[22:23], off offset:2048
	global_load_dwordx4 v[22:25], v[16:17], off
	v_mov_b32_e32 v28, v70
	v_mov_b32_e32 v29, v36
	v_mov_b32_e32 v36, v71
	v_pk_mul_f32 v[28:29], v[40:41], v[28:29] op_sel_hi:[0,1]
	v_pk_mul_f32 v[30:31], v[40:41], v[36:37] op_sel_hi:[0,1]
	s_waitcnt vmcnt(0)
	v_pk_mul_f32 v[22:23], v[28:29], v[22:23]
	v_pk_mul_f32 v[24:25], v[30:31], v[24:25]
	v_cvt_pk_bf16_f32 v22, v22, v23
	v_cvt_pk_bf16_f32 v23, v24, v25
	global_store_dwordx2 v[26:27], v[22:23], off offset:2560
	global_load_dwordx4 v[22:25], v[18:19], off
	v_pk_mul_f32 v[28:29], v[40:41], v[74:75] op_sel_hi:[0,1]
	v_pk_mul_f32 v[30:31], v[40:41], v[32:33] op_sel_hi:[0,1]
	s_waitcnt vmcnt(0)
	v_pk_mul_f32 v[22:23], v[28:29], v[22:23]
	v_pk_mul_f32 v[24:25], v[30:31], v[24:25]
	v_cvt_pk_bf16_f32 v22, v22, v23
	v_cvt_pk_bf16_f32 v23, v24, v25
	global_store_dwordx2 v[26:27], v[22:23], off offset:3072
	global_load_dwordx4 v[22:25], v[20:21], off
	v_pk_mul_f32 v[28:29], v[40:41], v[80:81] op_sel_hi:[0,1]
	v_pk_mul_f32 v[30:31], v[40:41], v[84:85] op_sel_hi:[0,1]
	s_waitcnt vmcnt(0)
	v_pk_mul_f32 v[22:23], v[28:29], v[22:23]
	v_pk_mul_f32 v[24:25], v[30:31], v[24:25]
	v_cvt_pk_bf16_f32 v22, v22, v23
	v_cvt_pk_bf16_f32 v23, v24, v25
	global_store_dwordx2 v[26:27], v[22:23], off offset:3584
	s_branch .LBB0_1074

; #define GAS __attribute__((address_space(1)))
; __device__ __forceinline__ float bflo(unsigned u) { return __uint_as_float(u << 16); }
; __device__ __forceinline__ float bfhi(unsigned u) { return __uint_as_float(u & 0xffff0000u); }
; template <bool XIN_BF, bool XOUT_BF>
; __device__ __forceinline__ void rows_update_g(const Ctx& C, const float* xin, const bf16* xin_bf, const bf16* Y, const float* wpost, float scale, float* xout, bf16* xout_bf, const float* wpre, bf16* HN) {
;     ...
;     for (int m = gw; m < T; m += NGW) {
;         const GAS v2u* yr = (const GAS v2u*)(Y + (size_t)m * D) + C.lane;
;         f32x4 v[8]; float s = 0.f;
; #pragma unroll
;         for (int j = 0; j < 8; ++j) { const v2u w = yr[64 * j]; v[j] = (f32x4){bflo(w.x), bfhi(w.x), bflo(w.y), bfhi(w.y)}; s += (v[j].x * v[j].x + v[j].y * v[j].y) + (v[j].z * v[j].z + v[j].w * v[j].w); }
;         const float rstd = scale / sqrtf(wave_sum(s) * (1.0f / D) + EPS);
.LBB0_1271:
	v_add_co_u32_e32 v14, vcc, 0xf8000000, v12
	global_load_dwordx4 v[32:35], v[0:1], off
	global_load_dwordx2 v[16:17], v[12:13], off offset:-3584
	v_addc_co_u32_e32 v15, vcc, -1, v13, vcc
	global_load_dwordx2 v[18:19], v[14:15], off offset:-3584
	global_load_dwordx2 v[20:21], v[14:15], off offset:-3072
	global_load_dwordx2 v[22:23], v[14:15], off offset:-2560
	global_load_dwordx2 v[36:37], v[14:15], off offset:-2048
	global_load_dwordx2 v[38:39], v[14:15], off offset:-1536
	global_load_dwordx2 v[40:41], v[14:15], off offset:-1024
	global_load_dwordx2 v[42:43], v[14:15], off offset:-512
	global_load_dwordx2 v[44:45], v[14:15], off
	s_add_i32 s6, s6, s92
	s_cmpk_lt_i32 s6, 0x4000
	s_waitcnt vmcnt(7)
	v_and_b32_e32 v51, 0xffff0000, v18
	v_and_b32_e32 v53, 0xffff0000, v19
	v_lshlrev_b32_e32 v50, 16, v18
	v_lshlrev_b32_e32 v52, 16, v19
	v_lshlrev_b32_e32 v46, 16, v16
	v_and_b32_e32 v47, 0xffff0000, v16
	v_lshlrev_b32_e32 v48, 16, v17
	v_and_b32_e32 v49, 0xffff0000, v17
	s_waitcnt vmcnt(6)
	v_and_b32_e32 v57, 0xffff0000, v21
	v_and_b32_e32 v56, 0xffff0000, v20
	s_waitcnt vmcnt(5)
	v_and_b32_e32 v59, 0xffff0000, v22
	v_and_b32_e32 v61, 0xffff0000, v23
	s_waitcnt vmcnt(4)
	v_lshlrev_b32_e32 v63, 16, v36
	s_waitcnt vmcnt(0)
	v_lshlrev_b32_e32 v19, 16, v44
	v_and_b32_e32 v17, 0xffff0000, v44
	v_mul_f32_e32 v16, v53, v53
	v_mul_f32_e32 v18, v51, v51
	v_lshlrev_b32_e32 v55, 16, v21
	v_lshlrev_b32_e32 v54, 16, v20
	v_lshlrev_b32_e32 v58, 16, v22
	v_lshlrev_b32_e32 v60, 16, v23
	v_lshlrev_b32_e32 v20, 16, v42
	v_and_b32_e32 v21, 0xffff0000, v42
	v_lshlrev_b32_e32 v22, 16, v43
	v_and_b32_e32 v23, 0xffff0000, v43
	v_lshlrev_b32_e32 v14, 16, v45
	v_and_b32_e32 v15, 0xffff0000, v45
	v_pk_mul_f32 v[42:43], v[56:57], v[56:57]
	v_mov_b32_e32 v45, v63
	v_mul_f32_e32 v44, v59, v59
	v_mul_f32_e32 v62, v61, v61
	v_pk_fma_f32 v[76:77], v[52:53], v[52:53], v[16:17] op_sel_hi:[1,1,0]
	v_pk_fma_f32 v[78:79], v[50:51], v[50:51], v[18:19] op_sel_hi:[1,1,0]
	v_and_b32_e32 v65, 0xffff0000, v36
	v_lshlrev_b32_e32 v36, 16, v37
	v_and_b32_e32 v37, 0xffff0000, v37
	v_pk_fma_f32 v[42:43], v[54:55], v[54:55], v[42:43]
	v_pk_fma_f32 v[80:81], v[58:59], v[58:59], v[44:45] op_sel_hi:[1,1,0]
	v_pk_fma_f32 v[82:83], v[60:61], v[60:61], v[62:63] op_sel_hi:[1,1,0]
	v_mov_b32_e32 v62, v78
	v_mov_b32_e32 v44, v76
	v_mul_f32_e32 v88, v65, v65
	v_mul_f32_e32 v89, v36, v36
	v_mul_f32_e32 v90, v37, v37
	v_pk_add_f32 v[76:77], v[78:79], v[76:77]
	v_pk_add_f32 v[42:43], v[42:43], v[42:43] op_sel:[0,1] op_sel_hi:[1,0]
	v_pk_mul_f32 v[44:45], v[62:63], v[44:45]
	v_lshlrev_b32_e32 v67, 16, v39
	v_lshlrev_b32_e32 v66, 16, v38
	v_and_b32_e32 v39, 0xffff0000, v39
	v_and_b32_e32 v38, 0xffff0000, v38
	v_mov_b32_e32 v81, v89
	v_mov_b32_e32 v83, v90
	v_mov_b32_e32 v43, v88
	v_mov_b32_e32 v77, v45
	v_pk_mul_f32 v[70:71], v[38:39], v[38:39]
	v_pk_add_f32 v[78:79], v[80:81], v[82:83]
	v_pk_add_f32 v[42:43], v[76:77], v[42:43]
	v_lshlrev_b32_e32 v69, 16, v41
	v_lshlrev_b32_e32 v68, 16, v40
	v_and_b32_e32 v41, 0xffff0000, v41
	v_and_b32_e32 v40, 0xffff0000, v40
	v_pk_fma_f32 v[70:71], v[66:67], v[66:67], v[70:71]
	v_pk_add_f32 v[42:43], v[42:43], v[78:79]
	v_pk_mul_f32 v[72:73], v[40:41], v[40:41]
	v_mov_b32_e32 v75, v19
	v_mul_f32_e32 v74, v23, v23
	v_pk_add_f32 v[70:71], v[70:71], v[70:71] op_sel:[0,1] op_sel_hi:[1,0]
	v_pk_add_f32 v[42:43], v[42:43], v[42:43] op_sel:[0,1] op_sel_hi:[1,0]
	v_mul_f32_e32 v64, v21, v21
	v_pk_fma_f32 v[72:73], v[68:69], v[68:69], v[72:73]
	v_pk_fma_f32 v[86:87], v[22:23], v[22:23], v[74:75] op_sel_hi:[1,1,0]
	v_mov_b32_e32 v74, v70
	v_mov_b32_e32 v18, v42
	v_mul_f32_e32 v91, v17, v17
	v_mul_f32_e32 v92, v14, v14
	v_mul_f32_e32 v93, v15, v15
	v_pk_fma_f32 v[84:85], v[20:21], v[20:21], v[64:65] op_sel_hi:[1,1,0]
	v_pk_add_f32 v[72:73], v[72:73], v[72:73] op_sel:[0,1] op_sel_hi:[1,0]
	v_pk_add_f32 v[42:43], v[42:43], v[70:71]
	v_pk_mul_f32 v[44:45], v[18:19], v[74:75]
	v_mov_b32_e32 v85, v92
	v_mov_b32_e32 v87, v93
	v_mov_b32_e32 v73, v91
	v_mov_b32_e32 v43, v45
	v_pk_add_f32 v[80:81], v[84:85], v[86:87]
	v_pk_add_f32 v[42:43], v[42:43], v[72:73]
	v_mov_b32_e32 v64, v63
	v_pk_add_f32 v[42:43], v[42:43], v[80:81]
	s_nop 0
	v_add_f32_e32 v16, v42, v43
	s_nop 1
	v_add_f32_dpp v16, v16, v16 quad_perm:[1,0,3,2] row_mask:0xf bank_mask:0xf
	s_nop 1
	v_add_f32_dpp v16, v16, v16 quad_perm:[2,3,0,1] row_mask:0xf bank_mask:0xf
	s_nop 1
	v_add_f32_dpp v16, v16, v16 row_half_mirror row_mask:0xf bank_mask:0xf
	s_nop 1
	v_add_f32_dpp v16, v16, v16 row_mirror row_mask:0xf bank_mask:0xf
	ds_bpermute_b32 v18, v28, v16
	s_waitcnt lgkmcnt(0)
; #define GAS __attribute__((address_space(1)))
; __device__ __forceinline__ unsigned pk2(float lo, float hi) { f32x2_t v = {lo, hi}; bf16x2_t b = __builtin_convertvector(v, bf16x2_t); return __builtin_bit_cast(unsigned, b); }
; __device__ __forceinline__ float bflo(unsigned u) { return __uint_as_float(u << 16); }
; __device__ __forceinline__ float bfhi(unsigned u) { return __uint_as_float(u & 0xffff0000u); }
; template <bool XIN_BF, bool XOUT_BF>
; __device__ __forceinline__ void rows_update_g(const Ctx& C, const float* xin, const bf16* xin_bf, const bf16* Y, const float* wpost, float scale, float* xout, bf16* xout_bf, const float* wpre, bf16* HN) {
;     ...
;         const float rstd = scale / sqrtf(wave_sum(s) * (1.0f / D) + EPS);
;         float s2 = 0.f;
; #pragma unroll
;         for (int j = 0; j < 8; ++j) { const f32x4 ww = *((const GAS f32x4*)wpost + C.lane + 64 * j); f32x4 xv;
;             if (XIN_BF) { const v2u xw = *((const GAS v2u*)(xin_bf + (size_t)m * D) + C.lane + 64 * j); xv = (f32x4){bflo(xw.x), bfhi(xw.x), bflo(xw.y), bfhi(xw.y)}; }
;             else xv = *((const GAS f32x4*)(xin + (size_t)m * D) + C.lane + 64 * j);
;             v[j] = xv + v[j] * rstd * ww;
;             if (XOUT_BF) { const v2u ow = (v2u){pk2(v[j].x, v[j].y), pk2(v[j].z, v[j].w)}; *((GAS v2u*)(xout_bf + (size_t)m * D) + C.lane + 64 * j) = ow;
;                 v[j] = (f32x4){bflo(ow.x), bfhi(ow.x), bflo(ow.y), bfhi(ow.y)}; }
;             else *((GAS f32x4*)(xout + (size_t)m * D) + C.lane + 64 * j) = v[j];
;             s2 += (v[j].x * v[j].x + v[j].y * v[j].y) + (v[j].z * v[j].z + v[j].w * v[j].w); }
	v_add_f32_e32 v16, v16, v18
	v_mov_b32_e32 v18, v16
	s_nop 1
	v_permlane32_swap_b32_e32 v18, v16
	v_add_f32_e32 v16, v16, v18
	v_fmamk_f32 v16, v16, 0x3a000000, v30
	v_mul_f32_e32 v18, 0x4f800000, v16
	v_cmp_gt_f32_e32 vcc, s7, v16
	s_nop 1
	v_cndmask_b32_e32 v16, v16, v18, vcc
	v_sqrt_f32_e32 v18, v16
	s_nop 0
	v_add_u32_e32 v42, -1, v18
	v_add_u32_e32 v43, 1, v18
	v_fma_f32 v44, -v42, v18, v16
	v_fma_f32 v45, -v43, v18, v16
	v_cmp_ge_f32_e64 s[0:1], 0, v44
	s_nop 1
	v_cndmask_b32_e64 v18, v18, v42, s[0:1]
	v_cmp_lt_f32_e64 s[0:1], 0, v45
	s_nop 1
	v_cndmask_b32_e64 v18, v18, v43, s[0:1]
	v_mul_f32_e32 v42, 0x37800000, v18
	v_cndmask_b32_e32 v18, v18, v42, vcc
	v_cmp_class_f32_e32 vcc, v16, v31
	s_nop 1
	v_cndmask_b32_e32 v16, v18, v16, vcc
	v_div_scale_f32 v18, s[0:1], v16, v16, 0.5
	v_rcp_f32_e32 v43, v18
	v_div_scale_f32 v42, vcc, 0.5, v16, 0.5
	v_fma_f32 v44, -v18, v43, 1.0
	v_fmac_f32_e32 v43, v44, v43
	v_mul_f32_e32 v44, v42, v43
	v_fma_f32 v45, -v18, v44, v42
	v_fmac_f32_e32 v44, v45, v43
	v_fma_f32 v18, -v18, v44, v42
	v_div_fmas_f32 v18, v18, v43, v44
	v_div_fixup_f32 v18, v18, v16, 0.5
	v_pk_mul_f32 v[42:43], v[18:19], v[50:51] op_sel_hi:[0,1]
	v_pk_mul_f32 v[44:45], v[18:19], v[52:53] op_sel_hi:[0,1]
	v_pk_fma_f32 v[34:35], v[34:35], v[44:45], v[48:49]
	v_pk_fma_f32 v[32:33], v[32:33], v[42:43], v[46:47]
	global_store_dwordx4 v[10:11], v[32:35], off offset:-4096
	global_load_dwordx2 v[42:43], v[12:13], off offset:-3072
	s_nop 0
	global_load_dwordx4 v[32:35], v[0:1], off offset:1024
	v_mov_b32_e32 v44, v54
	v_mov_b32_e32 v45, v56
	v_mov_b32_e32 v56, v55
	v_pk_mul_f32 v[44:45], v[18:19], v[44:45] op_sel_hi:[0,1]
	v_pk_mul_f32 v[46:47], v[18:19], v[56:57] op_sel_hi:[0,1]
	v_pk_mul_f32 v[36:37], v[36:37], v[18:19] op_sel_hi:[1,0]
	v_pk_mul_f32 v[20:21], v[18:19], v[20:21] op_sel_hi:[0,1]
	v_pk_mul_f32 v[22:23], v[18:19], v[22:23] op_sel_hi:[0,1]
	v_mov_b32_e32 v16, v19
	v_pk_mul_f32 v[14:15], v[14:15], v[18:19] op_sel_hi:[1,0]
	s_waitcnt vmcnt(1)
	v_lshlrev_b32_e32 v48, 16, v42
	v_and_b32_e32 v49, 0xffff0000, v42
	v_lshlrev_b32_e32 v42, 16, v43
	v_and_b32_e32 v43, 0xffff0000, v43
	s_waitcnt vmcnt(0)
	v_pk_fma_f32 v[34:35], v[34:35], v[46:47], v[42:43]
	v_pk_fma_f32 v[32:33], v[32:33], v[44:45], v[48:49]
	global_store_dwordx4 v[10:11], v[32:35], off offset:-3072
	global_load_dwordx2 v[42:43], v[12:13], off offset:-2560
	s_nop 0
	global_load_dwordx4 v[32:35], v[0:1], off offset:2048
	v_pk_mul_f32 v[44:45], v[18:19], v[58:59] op_sel_hi:[0,1]
	v_pk_mul_f32 v[46:47], v[18:19], v[60:61] op_sel_hi:[0,1]
	s_waitcnt vmcnt(1)
	v_lshlrev_b32_e32 v48, 16, v42
	v_and_b32_e32 v49, 0xffff0000, v42
	v_lshlrev_b32_e32 v42, 16, v43
	v_and_b32_e32 v43, 0xffff0000, v43
	s_waitcnt vmcnt(0)
	v_pk_fma_f32 v[34:35], v[34:35], v[46:47], v[42:43]
	v_pk_fma_f32 v[32:33], v[32:33], v[44:45], v[48:49]
	global_store_dwordx4 v[10:11], v[32:35], off offset:-2048
	global_load_dwordx2 v[42:43], v[12:13], off offset:-2048
	s_nop 0
	global_load_dwordx4 v[32:35], v[0:1], off offset:3072
	v_pk_mul_f32 v[44:45], v[64:65], v[18:19] op_sel_hi:[1,0]
	s_waitcnt vmcnt(1)
	v_lshlrev_b32_e32 v46, 16, v42
	v_and_b32_e32 v47, 0xffff0000, v42
	v_lshlrev_b32_e32 v42, 16, v43
	v_and_b32_e32 v43, 0xffff0000, v43
	s_waitcnt vmcnt(0)
	v_pk_fma_f32 v[34:35], v[34:35], v[36:37], v[42:43]
	v_pk_fma_f32 v[32:33], v[32:33], v[44:45], v[46:47]
	global_store_dwordx4 v[10:11], v[32:35], off offset:-1024
	global_load_dwordx2 v[36:37], v[12:13], off offset:-1536
	s_nop 0
	global_load_dwordx4 v[32:35], v[2:3], off
	v_mov_b32_e32 v42, v66
	v_mov_b32_e32 v43, v38
	v_mov_b32_e32 v38, v67
	v_pk_mul_f32 v[42:43], v[18:19], v[42:43] op_sel_hi:[0,1]
	v_pk_mul_f32 v[38:39], v[18:19], v[38:39] op_sel_hi:[0,1]
	s_waitcnt vmcnt(1)
	v_lshlrev_b32_e32 v44, 16, v36
	v_and_b32_e32 v45, 0xffff0000, v36
	v_lshlrev_b32_e32 v36, 16, v37
	v_and_b32_e32 v37, 0xffff0000, v37
	s_waitcnt vmcnt(0)
	v_pk_fma_f32 v[34:35], v[34:35], v[38:39], v[36:37]
	v_pk_fma_f32 v[32:33], v[32:33], v[42:43], v[44:45]
	global_store_dwordx4 v[10:11], v[32:35], off
	global_load_dwordx2 v[36:37], v[12:13], off offset:-1024
	s_nop 0
	global_load_dwordx4 v[32:35], v[4:5], off
	v_mov_b32_e32 v38, v68
	v_mov_b32_e32 v39, v40
	v_mov_b32_e32 v40, v69
	v_pk_mul_f32 v[38:39], v[18:19], v[38:39] op_sel_hi:[0,1]
	v_pk_mul_f32 v[40:41], v[18:19], v[40:41] op_sel_hi:[0,1]
	s_waitcnt vmcnt(1)
	v_lshlrev_b32_e32 v42, 16, v36
	v_and_b32_e32 v43, 0xffff0000, v36
	v_lshlrev_b32_e32 v36, 16, v37
	v_and_b32_e32 v37, 0xffff0000, v37
	s_waitcnt vmcnt(0)
	v_pk_fma_f32 v[34:35], v[40:41], v[34:35], v[36:37]
	v_pk_fma_f32 v[32:33], v[38:39], v[32:33], v[42:43]
	global_store_dwordx4 v[10:11], v[32:35], off offset:1024
	global_load_dwordx2 v[36:37], v[12:13], off offset:-512
	s_nop 0
	global_load_dwordx4 v[32:35], v[6:7], off
	s_waitcnt vmcnt(1)
	v_lshlrev_b32_e32 v38, 16, v36
	v_and_b32_e32 v39, 0xffff0000, v36
	v_lshlrev_b32_e32 v36, 16, v37
	v_and_b32_e32 v37, 0xffff0000, v37
	s_waitcnt vmcnt(0)
	v_pk_fma_f32 v[22:23], v[22:23], v[34:35], v[36:37]
	v_pk_fma_f32 v[20:21], v[20:21], v[32:33], v[38:39]
	global_store_dwordx4 v[10:11], v[20:23], off offset:2048
	global_load_dwordx2 v[32:33], v[12:13], off
	s_nop 0
	global_load_dwordx4 v[20:23], v[8:9], off
	v_pk_mul_f32 v[34:35], v[16:17], v[18:19] op_sel_hi:[1,0]
	v_lshl_add_u64 v[12:13], v[12:13], 0, s[4:5]
	s_waitcnt vmcnt(1)
	v_lshlrev_b32_e32 v18, 16, v32
	v_and_b32_e32 v19, 0xffff0000, v32
	v_lshlrev_b32_e32 v16, 16, v33
	v_and_b32_e32 v17, 0xffff0000, v33
	s_waitcnt vmcnt(0)
	v_pk_fma_f32 v[16:17], v[14:15], v[22:23], v[16:17]
	v_pk_fma_f32 v[14:15], v[34:35], v[20:21], v[18:19]
	global_store_dwordx4 v[10:11], v[14:17], off offset:3072
	v_lshl_add_u64 v[10:11], v[10:11], 0, s[2:3]
	s_cbranch_scc1 .LBB0_1271
